# previous + every row/head sum s += shfl_xor(s,16|32) (45 sites in the GEMM epilogues and q loaders) done with v_permlane16/32_swap instead of ds_bpermute (no LDS round trip), bit-identical
# baseline (speedup 1.0000x reference)
; #define GAS __attribute__((address_space(1)))
; __device__ __forceinline__ unsigned pkh(float lo, float hi) { f32x2 v = {lo, hi}; h16x2 h = __builtin_convertvector(v, h16x2); return __builtin_bit_cast(unsigned, h); }
; __device__ __forceinline__ float wave_sum(float v) {
; #pragma unroll
;     for (int o = 1; o < 64; o <<= 1) v += __shfl_xor(v, o);
;     return v;
; __device__ __forceinline__ void p0_prologue(const Frame& F, const Args& a) {
;     ...
;         for (int m0 = gw; m0 < M; m0 += 4 * NGW) {
;             f32x4 v[4][4];
; #pragma unroll
;             for (int r = 0; r < 4; ++r) { const int mm = (m0 + r * NGW < M) ? m0 + r * NGW : m0; const GAS f32x4* xr = (const GAS f32x4*)(x + (size_t)mm * DM) + F.lane;
; #pragma unroll
;                 for (int j = 0; j < 4; ++j) v[r][j] = __builtin_nontemporal_load(xr + 64 * j); }
; #pragma unroll
;             for (int r = 0; r < 4; ++r) { const int m = m0 + r * NGW; if (m >= M) break; float s = 0.f;
; #pragma unroll
;                 for (int j = 0; j < 4; ++j) s += (v[r][j].x * v[r][j].x + v[r][j].y * v[r][j].y) + (v[r][j].z * v[r][j].z + v[r][j].w * v[r][j].w);
;                 s = wave_sum(s);
;                 if (F.lane == 0) ss0[m] = s;
;                 GAS u32x2* o8 = (GAS u32x2*)(A16 + (size_t)m * DM) + F.lane;
; #pragma unroll
;                 for (int j = 0; j < 4; ++j) { u32x2 w; w.x = pkh(v[r][j].x, v[r][j].y); w.y = pkh(v[r][j].z, v[r][j].w); o8[64 * j] = w; } }
.LBB0_58:
	s_ashr_i32 s31, s30, 31
	s_lshl_b64 s[4:5], s[30:31], 12
	s_waitcnt vmcnt(4)
	v_lshl_add_u64 v[2:3], v[68:69], 0, s[4:5]
	global_load_dwordx4 v[62:65], v[2:3], off nt
	global_load_dwordx4 v[58:61], v[2:3], off offset:1024 nt
	global_load_dwordx4 v[54:57], v[2:3], off offset:2048 nt
	global_load_dwordx4 v[50:53], v[2:3], off offset:3072 nt
	s_add_i32 s4, s30, s24
	s_cmp_lt_i32 s4, 0x8000
	s_cselect_b64 s[28:29], -1, 0
	s_and_b64 s[8:9], s[28:29], exec
	s_cselect_b32 s8, s4, s30
	s_ashr_i32 s9, s8, 31
	s_add_i32 s12, s25, s30
	s_lshl_b64 s[8:9], s[8:9], 12
	s_cmp_lt_i32 s12, 0x8000
	s_cselect_b64 s[26:27], -1, 0
	v_lshl_add_u64 v[2:3], v[68:69], 0, s[8:9]
	s_and_b64 s[8:9], s[26:27], exec
	s_cselect_b32 s18, s12, s30
	s_ashr_i32 s19, s18, 31
	s_add_i32 s8, s36, s30
	s_lshl_b64 s[18:19], s[18:19], 12
	s_cmp_lt_i32 s8, 0x8000
	global_load_dwordx4 v[46:49], v[2:3], off nt
	global_load_dwordx4 v[42:45], v[2:3], off offset:1024 nt
	global_load_dwordx4 v[38:41], v[2:3], off offset:2048 nt
	global_load_dwordx4 v[34:37], v[2:3], off offset:3072 nt
	v_lshl_add_u64 v[2:3], v[68:69], 0, s[18:19]
	s_cselect_b64 s[18:19], -1, 0
	s_and_b64 s[34:35], s[18:19], exec
	s_cselect_b32 s34, s8, s30
	s_ashr_i32 s35, s34, 31
	s_lshl_b64 s[34:35], s[34:35], 12
	global_load_dwordx4 v[30:33], v[2:3], off nt
	global_load_dwordx4 v[26:29], v[2:3], off offset:1024 nt
	global_load_dwordx4 v[22:25], v[2:3], off offset:2048 nt
	global_load_dwordx4 v[18:21], v[2:3], off offset:3072 nt
	v_lshl_add_u64 v[2:3], v[68:69], 0, s[34:35]
	global_load_dwordx4 v[14:17], v[2:3], off nt
	global_load_dwordx4 v[10:13], v[2:3], off offset:1024 nt
	global_load_dwordx4 v[6:9], v[2:3], off offset:2048 nt
	s_nop 0
	global_load_dwordx4 v[2:5], v[2:3], off offset:3072 nt
	s_waitcnt vmcnt(15)
	v_mul_f32_e32 v66, v63, v63
	s_waitcnt lgkmcnt(0)
	v_mul_f32_e32 v77, v65, v65
	s_waitcnt vmcnt(14)
	v_mul_f32_e32 v78, v59, v59
	v_mul_f32_e32 v79, v61, v61
	s_waitcnt vmcnt(13)
	v_mul_f32_e32 v80, v55, v55
	v_mul_f32_e32 v81, v57, v57
	v_fmac_f32_e32 v66, v62, v62
	v_fmac_f32_e32 v77, v64, v64
	v_fmac_f32_e32 v78, v58, v58
	v_fmac_f32_e32 v79, v60, v60
	s_waitcnt vmcnt(12)
	v_mul_f32_e32 v82, v51, v51
	v_mul_f32_e32 v83, v53, v53
	v_fmac_f32_e32 v80, v54, v54
	v_fmac_f32_e32 v81, v56, v56
	v_add_f32_e32 v66, v66, v77
	v_add_f32_e32 v77, v78, v79
	v_fmac_f32_e32 v82, v50, v50
	v_fmac_f32_e32 v83, v52, v52
	v_add_f32_e32 v78, v80, v81
	v_add_f32_e32 v66, v66, v77
	v_add_f32_e32 v66, v66, v78
	v_add_f32_e32 v77, v82, v83
	v_add_f32_e32 v66, v66, v77
	ds_bpermute_b32 v77, v1, v66
	s_waitcnt lgkmcnt(0)
	v_add_f32_e32 v66, v66, v77
	ds_bpermute_b32 v77, v72, v66
	s_waitcnt lgkmcnt(0)
	v_add_f32_e32 v66, v66, v77
	ds_bpermute_b32 v77, v73, v66
	s_waitcnt lgkmcnt(0)
	v_add_f32_e32 v66, v66, v77
	ds_bpermute_b32 v77, v74, v66
	s_waitcnt lgkmcnt(0)
	v_add_f32_e32 v66, v66, v77
	v_mov_b32_e32 v77, v66
	s_nop 1
	v_permlane16_swap_b32_e32 v66, v77
	v_add_f32_e32 v66, v66, v77
	ds_bpermute_b32 v77, v76, v66
	s_and_saveexec_b64 s[34:35], s[0:1]
	s_cbranch_execz .LBB0_60
	s_lshl_b64 s[38:39], s[30:31], 2
	s_add_u32 s38, s20, s38
	s_waitcnt lgkmcnt(0)
	v_add_f32_e32 v66, v66, v77
	s_addc_u32 s39, s21, s39
	global_store_dword v67, v66, s[38:39]
.LBB0_60:
	s_or_b64 exec, exec, s[34:35]
	s_lshl_b64 s[30:31], s[30:31], 11
	v_lshl_add_u64 v[78:79], v[70:71], 0, s[30:31]
	v_cvt_pk_f16_f32 v62, v62, v63
	v_cvt_pk_f16_f32 v63, v64, v65
	v_cvt_pk_f16_f32 v58, v58, v59
	v_cvt_pk_f16_f32 v59, v60, v61
	v_cvt_pk_f16_f32 v54, v54, v55
	v_cvt_pk_f16_f32 v55, v56, v57
	v_cvt_pk_f16_f32 v50, v50, v51
	v_cvt_pk_f16_f32 v51, v52, v53
	s_andn2_b64 vcc, exec, s[28:29]
	global_store_dwordx2 v[78:79], v[62:63], off
	global_store_dwordx2 v[78:79], v[58:59], off offset:512
	global_store_dwordx2 v[78:79], v[54:55], off offset:1024
	global_store_dwordx2 v[78:79], v[50:51], off offset:1536
	s_cbranch_vccnz .LBB0_57
	s_waitcnt vmcnt(15)
	v_mul_f32_e32 v50, v47, v47
	v_mul_f32_e32 v51, v49, v49
	v_fmac_f32_e32 v50, v46, v46
	v_fmac_f32_e32 v51, v48, v48
	v_add_f32_e32 v50, v50, v51
	s_waitcnt vmcnt(14)
	v_mul_f32_e32 v51, v43, v43
	v_mul_f32_e32 v52, v45, v45
	v_fmac_f32_e32 v51, v42, v42
	v_fmac_f32_e32 v52, v44, v44
	v_add_f32_e32 v51, v51, v52
	v_add_f32_e32 v50, v50, v51
	s_waitcnt vmcnt(13)
	v_mul_f32_e32 v51, v39, v39
	v_mul_f32_e32 v52, v41, v41
	v_fmac_f32_e32 v51, v38, v38
	v_fmac_f32_e32 v52, v40, v40
	v_add_f32_e32 v51, v51, v52
	v_add_f32_e32 v50, v50, v51
	s_waitcnt vmcnt(12)
	v_mul_f32_e32 v51, v35, v35
	v_mul_f32_e32 v52, v37, v37
	v_fmac_f32_e32 v51, v34, v34
	v_fmac_f32_e32 v52, v36, v36
	v_add_f32_e32 v51, v51, v52
	v_add_f32_e32 v50, v50, v51
	ds_bpermute_b32 v51, v1, v50
	s_ashr_i32 s5, s4, 31
	s_waitcnt lgkmcnt(0)
	v_add_f32_e32 v50, v50, v51
	ds_bpermute_b32 v51, v72, v50
	s_waitcnt lgkmcnt(0)
	v_add_f32_e32 v50, v50, v51
	ds_bpermute_b32 v51, v73, v50
	s_waitcnt lgkmcnt(0)
	v_add_f32_e32 v50, v50, v51
	ds_bpermute_b32 v51, v74, v50
	s_waitcnt lgkmcnt(0)
	v_add_f32_e32 v50, v50, v51
	v_mov_b32_e32 v51, v50
	s_nop 1
	v_permlane16_swap_b32_e32 v50, v51
	v_add_f32_e32 v50, v50, v51
	ds_bpermute_b32 v51, v76, v50
	s_and_saveexec_b64 s[28:29], s[0:1]
	s_cbranch_execz .LBB0_63
	s_lshl_b64 s[30:31], s[4:5], 2
	s_add_u32 s30, s20, s30
	s_waitcnt lgkmcnt(0)
	v_add_f32_e32 v50, v50, v51
	s_addc_u32 s31, s21, s31
	global_store_dword v67, v50, s[30:31]
; #define GAS __attribute__((address_space(1)))
; __device__ __forceinline__ unsigned pkh(float lo, float hi) { f32x2 v = {lo, hi}; h16x2 h = __builtin_convertvector(v, h16x2); return __builtin_bit_cast(unsigned, h); }
; __device__ __forceinline__ float wave_sum(float v) {
; #pragma unroll
;     for (int o = 1; o < 64; o <<= 1) v += __shfl_xor(v, o);
;     return v;
; __device__ __forceinline__ void p0_prologue(const Frame& F, const Args& a) {
;     ...
;             for (int r = 0; r < 4; ++r) { const int m = m0 + r * NGW; if (m >= M) break; float s = 0.f;
; #pragma unroll
;                 for (int j = 0; j < 4; ++j) s += (v[r][j].x * v[r][j].x + v[r][j].y * v[r][j].y) + (v[r][j].z * v[r][j].z + v[r][j].w * v[r][j].w);
;                 s = wave_sum(s);
;                 if (F.lane == 0) ss0[m] = s;
;                 GAS u32x2* o8 = (GAS u32x2*)(A16 + (size_t)m * DM) + F.lane;
; #pragma unroll
;                 for (int j = 0; j < 4; ++j) { u32x2 w; w.x = pkh(v[r][j].x, v[r][j].y); w.y = pkh(v[r][j].z, v[r][j].w); o8[64 * j] = w; } }
.LBB0_63:
	s_or_b64 exec, exec, s[28:29]
	s_lshl_b64 s[28:29], s[4:5], 11
	s_waitcnt lgkmcnt(0)
	v_lshl_add_u64 v[50:51], v[70:71], 0, s[28:29]
	v_cvt_pk_f16_f32 v46, v46, v47
	v_cvt_pk_f16_f32 v47, v48, v49
	v_cvt_pk_f16_f32 v42, v42, v43
	v_cvt_pk_f16_f32 v43, v44, v45
	v_cvt_pk_f16_f32 v38, v38, v39
	v_cvt_pk_f16_f32 v39, v40, v41
	v_cvt_pk_f16_f32 v34, v34, v35
	v_cvt_pk_f16_f32 v35, v36, v37
	s_andn2_b64 vcc, exec, s[26:27]
	global_store_dwordx2 v[50:51], v[46:47], off
	global_store_dwordx2 v[50:51], v[42:43], off offset:512
	global_store_dwordx2 v[50:51], v[38:39], off offset:1024
	global_store_dwordx2 v[50:51], v[34:35], off offset:1536
	s_cbranch_vccnz .LBB0_57
	s_waitcnt vmcnt(15)
	v_mul_f32_e32 v34, v31, v31
	v_mul_f32_e32 v35, v33, v33
	v_fmac_f32_e32 v34, v30, v30
	v_fmac_f32_e32 v35, v32, v32
	v_add_f32_e32 v34, v34, v35
	s_waitcnt vmcnt(14)
	v_mul_f32_e32 v35, v27, v27
	v_mul_f32_e32 v36, v29, v29
	v_fmac_f32_e32 v35, v26, v26
	v_fmac_f32_e32 v36, v28, v28
	v_add_f32_e32 v35, v35, v36
	v_add_f32_e32 v34, v34, v35
	s_waitcnt vmcnt(13)
	v_mul_f32_e32 v35, v23, v23
	v_mul_f32_e32 v36, v25, v25
	v_fmac_f32_e32 v35, v22, v22
	v_fmac_f32_e32 v36, v24, v24
	v_add_f32_e32 v35, v35, v36
	v_add_f32_e32 v34, v34, v35
	s_waitcnt vmcnt(12)
	v_mul_f32_e32 v35, v19, v19
	v_mul_f32_e32 v36, v21, v21
	v_fmac_f32_e32 v35, v18, v18
	v_fmac_f32_e32 v36, v20, v20
	v_add_f32_e32 v35, v35, v36
	v_add_f32_e32 v34, v34, v35
	ds_bpermute_b32 v35, v1, v34
	s_ashr_i32 s13, s12, 31
	s_waitcnt lgkmcnt(0)
	v_add_f32_e32 v34, v34, v35
	ds_bpermute_b32 v35, v72, v34
	s_waitcnt lgkmcnt(0)
	v_add_f32_e32 v34, v34, v35
	ds_bpermute_b32 v35, v73, v34
	s_waitcnt lgkmcnt(0)
	v_add_f32_e32 v34, v34, v35
	ds_bpermute_b32 v35, v74, v34
	s_waitcnt lgkmcnt(0)
	v_add_f32_e32 v34, v34, v35
	v_mov_b32_e32 v35, v34
	s_nop 1
	v_permlane16_swap_b32_e32 v34, v35
	v_add_f32_e32 v34, v34, v35
	ds_bpermute_b32 v35, v76, v34
	s_and_saveexec_b64 s[26:27], s[0:1]
	s_cbranch_execz .LBB0_66
	s_lshl_b64 s[28:29], s[12:13], 2
	s_add_u32 s28, s20, s28
	s_waitcnt lgkmcnt(0)
	v_add_f32_e32 v34, v34, v35
	s_addc_u32 s29, s21, s29
	global_store_dword v67, v34, s[28:29]
.LBB0_66:
	s_or_b64 exec, exec, s[26:27]
	s_lshl_b64 s[12:13], s[12:13], 11
	s_waitcnt lgkmcnt(0)
	v_lshl_add_u64 v[34:35], v[70:71], 0, s[12:13]
	v_cvt_pk_f16_f32 v30, v30, v31
	v_cvt_pk_f16_f32 v31, v32, v33
	v_cvt_pk_f16_f32 v26, v26, v27
	v_cvt_pk_f16_f32 v27, v28, v29
	v_cvt_pk_f16_f32 v22, v22, v23
	v_cvt_pk_f16_f32 v23, v24, v25
	v_cvt_pk_f16_f32 v18, v18, v19
	v_cvt_pk_f16_f32 v19, v20, v21
	s_andn2_b64 vcc, exec, s[18:19]
	global_store_dwordx2 v[34:35], v[30:31], off
	global_store_dwordx2 v[34:35], v[26:27], off offset:512
	global_store_dwordx2 v[34:35], v[22:23], off offset:1024
	global_store_dwordx2 v[34:35], v[18:19], off offset:1536
	s_cbranch_vccnz .LBB0_57
	s_waitcnt vmcnt(15)
	v_mul_f32_e32 v18, v15, v15
	v_mul_f32_e32 v19, v17, v17
	v_fmac_f32_e32 v18, v14, v14
	v_fmac_f32_e32 v19, v16, v16
	v_add_f32_e32 v18, v18, v19
	s_waitcnt vmcnt(14)
	v_mul_f32_e32 v19, v11, v11
	v_mul_f32_e32 v20, v13, v13
	v_fmac_f32_e32 v19, v10, v10
	v_fmac_f32_e32 v20, v12, v12
	v_add_f32_e32 v19, v19, v20
	v_add_f32_e32 v18, v18, v19
	s_waitcnt vmcnt(13)
	v_mul_f32_e32 v19, v7, v7
	v_mul_f32_e32 v20, v9, v9
	v_fmac_f32_e32 v19, v6, v6
	v_fmac_f32_e32 v20, v8, v8
	v_add_f32_e32 v19, v19, v20
	v_add_f32_e32 v18, v18, v19
	s_waitcnt vmcnt(12)
	v_mul_f32_e32 v19, v3, v3
	v_mul_f32_e32 v20, v5, v5
	v_fmac_f32_e32 v19, v2, v2
	v_fmac_f32_e32 v20, v4, v4
	v_add_f32_e32 v19, v19, v20
	v_add_f32_e32 v18, v18, v19
	ds_bpermute_b32 v19, v1, v18
	s_ashr_i32 s9, s8, 31
	s_waitcnt lgkmcnt(0)
	v_add_f32_e32 v18, v18, v19
	ds_bpermute_b32 v19, v72, v18
	s_waitcnt lgkmcnt(0)
	v_add_f32_e32 v18, v18, v19
	ds_bpermute_b32 v19, v73, v18
	s_waitcnt lgkmcnt(0)
	v_add_f32_e32 v18, v18, v19
	ds_bpermute_b32 v19, v74, v18
	s_waitcnt lgkmcnt(0)
	v_add_f32_e32 v18, v18, v19
	v_mov_b32_e32 v19, v18
	s_nop 1
	v_permlane16_swap_b32_e32 v18, v19
	v_add_f32_e32 v18, v18, v19
	ds_bpermute_b32 v19, v76, v18
	s_and_saveexec_b64 s[12:13], s[0:1]
	s_cbranch_execz .LBB0_56
	s_lshl_b64 s[18:19], s[8:9], 2
	s_add_u32 s18, s20, s18
	s_waitcnt lgkmcnt(0)
	v_add_f32_e32 v18, v18, v19
	s_addc_u32 s19, s21, s19
	global_store_dword v67, v18, s[18:19]
	s_branch .LBB0_56

; #define GAS __attribute__((address_space(1)))
; __device__ __forceinline__ float wave_sum(float v) {
; #pragma unroll
;     for (int o = 1; o < 64; o <<= 1) v += __shfl_xor(v, o);
;     return v;
; __device__ __forceinline__ void p0_prologue(const Frame& F, const Args& a) {
;     ...
;         for (int m = gw; m < BATCH * NMEM; m += NGW) {
;             const GAS f32x4* xr = (const GAS f32x4*)(x + (size_t)m * DM) + F.lane;
;             f32x4 v[4]; float s = 0.f;
; #pragma unroll
;             for (int j = 0; j < 4; ++j) { v[j] = xr[64 * j]; s += (v[j].x * v[j].x + v[j].y * v[j].y) + (v[j].z * v[j].z + v[j].w * v[j].w); }
;             s = wave_sum(s);
;             if (F.lane == 0) ssm[m] = s;
.LBB0_72:
	global_load_dwordx4 v[6:9], v[22:23], off offset:-3072
	global_load_dwordx4 v[2:5], v[22:23], off offset:-2048
	global_load_dwordx4 v[10:13], v[22:23], off offset:-1024
	global_load_dwordx4 v[14:17], v[22:23], off
	s_waitcnt vmcnt(3)
	v_mul_f32_e32 v20, v7, v7
	s_waitcnt lgkmcnt(0)
	v_mul_f32_e32 v29, v9, v9
	s_waitcnt vmcnt(2)
	v_mul_f32_e32 v30, v3, v3
	v_mul_f32_e32 v31, v5, v5
	s_waitcnt vmcnt(1)
	v_mul_f32_e32 v32, v11, v11
	v_mul_f32_e32 v33, v13, v13
	v_fmac_f32_e32 v20, v6, v6
	v_fmac_f32_e32 v29, v8, v8
	v_fmac_f32_e32 v30, v2, v2
	v_fmac_f32_e32 v31, v4, v4
	s_waitcnt vmcnt(0)
	v_mul_f32_e32 v34, v15, v15
	v_mul_f32_e32 v35, v17, v17
	v_fmac_f32_e32 v32, v10, v10
	v_fmac_f32_e32 v33, v12, v12
	v_add_f32_e32 v20, v20, v29
	v_add_f32_e32 v29, v30, v31
	v_fmac_f32_e32 v34, v14, v14
	v_fmac_f32_e32 v35, v16, v16
	v_add_f32_e32 v30, v32, v33
	v_add_f32_e32 v20, v20, v29
	v_add_f32_e32 v20, v20, v30
	v_add_f32_e32 v29, v34, v35
	v_add_f32_e32 v20, v20, v29
	ds_bpermute_b32 v29, v1, v20
	s_waitcnt lgkmcnt(0)
	v_add_f32_e32 v20, v20, v29
	ds_bpermute_b32 v29, v24, v20
	s_waitcnt lgkmcnt(0)
	v_add_f32_e32 v20, v20, v29
	ds_bpermute_b32 v29, v25, v20
	s_waitcnt lgkmcnt(0)
	v_add_f32_e32 v20, v20, v29
	ds_bpermute_b32 v29, v26, v20
	s_waitcnt lgkmcnt(0)
	v_add_f32_e32 v20, v20, v29
	v_mov_b32_e32 v29, v20
	s_nop 1
	v_permlane16_swap_b32_e32 v20, v29
	v_add_f32_e32 v20, v20, v29
	ds_bpermute_b32 v29, v28, v20
	s_and_saveexec_b64 s[12:13], s[0:1]
	s_cbranch_execz .LBB0_71
	s_add_u32 s26, s76, s18
	s_waitcnt lgkmcnt(0)
	v_add_f32_e32 v20, v20, v29
	s_addc_u32 s27, s77, s19
	global_store_dword v21, v20, s[26:27]
	s_branch .LBB0_71

; __device__ __forceinline__ unsigned pkh(float lo, float hi) { f32x2 v = {lo, hi}; h16x2 h = __builtin_convertvector(v, h16x2); return __builtin_bit_cast(unsigned, h); }
;     __device__ __forceinline__ void operator()(f32x4 (&acc)[2][2][4][2], const Unit& u, const Order& S, int wr, int wc, int fr_, int fq_, LAS unsigned char*, int) const {
;     ...
;         for (int ai = 0; ai < 2; ++ai)
; #pragma unroll
;             for (int m = 0; m < 4; ++m) {
;                 const int key = ai * HALF + wr * 64 + m * 16 + fr;
;                 const float sc = __builtin_amdgcn_rsqf(ss_in[u.pm * BM + key] * (1.0f / DM) + EPS);
;                 f32x4 v[2][2]; float sq = 0.f;
; #pragma unroll
;                 for (int bj = 0; bj < 2; ++bj)
; #pragma unroll
;                     for (int n = 0; n < 2; ++n) { v[bj][n] = acc[ai][bj][m][n] * sc; const f32x4 t = v[bj][n]; sq += (t[0] * t[0] + t[1] * t[1]) + (t[2] * t[2] + t[3] * t[3]); }
;                 float rn = 1.f;
;                 if (isk) { sq += __shfl_xor(sq, 16); sq += __shfl_xor(sq, 32); rn = __builtin_amdgcn_rsqf(sq * (1.0f / HD) + EPS); }
; #pragma unroll
;                 for (int bj = 0; bj < 2; ++bj) {
;                     const f32x4 a = v[bj][0] * rn * gv[bj][0], b = v[bj][1] * rn * gv[bj][1];
;                     u32x4 w; w.x = pkh(a[0], a[1]); w.y = pkh(a[2], a[3]); w.z = pkh(b[0], b[1]); w.w = pkh(b[2], b[3]);
;                     *(u32x4*)(dst + (size_t)key * HD + 32 * bj + 8 * fq) = w;
;                 }
.LBB0_148:
	v_add_u32_e32 v158, s52, v160
	s_lshl_b32 s23, s67, 8
	v_add_u32_e32 v164, s23, v158
	v_ashrrev_i32_e32 v165, 31, v164
	v_lshl_add_u64 v[164:165], v[164:165], 2, s[4:5]
	global_load_dword v159, v[164:165], off
	v_mov_b32_e32 v160, 1.0
	s_and_b64 vcc, exec, s[0:1]
	s_waitcnt vmcnt(0)
	v_fmamk_f32 v159, v159, 0x3a800000, v174
	v_rsq_f32_e32 v166, v159
	s_nop 0
	v_pk_mul_f32 v[144:145], v[144:145], v[166:167] op_sel_hi:[1,0]
	v_pk_mul_f32 v[164:165], v[142:143], v[166:167] op_sel_hi:[1,0]
	v_pk_mul_f32 v[140:141], v[140:141], v[166:167] op_sel_hi:[1,0]
	v_pk_mul_f32 v[142:143], v[138:139], v[166:167] op_sel_hi:[1,0]
	v_pk_mul_f32 v[136:137], v[136:137], v[166:167] op_sel_hi:[1,0]
	v_pk_mul_f32 v[138:139], v[134:135], v[166:167] op_sel_hi:[1,0]
	v_pk_mul_f32 v[132:133], v[132:133], v[166:167] op_sel_hi:[1,0]
	v_pk_mul_f32 v[134:135], v[130:131], v[166:167] op_sel_hi:[1,0]
	v_mov_b32_e32 v166, 1.0
	s_cbranch_vccnz .LBB0_150
	v_pk_mul_f32 v[130:131], v[144:145], v[144:145]
	v_pk_mul_f32 v[176:177], v[164:165], v[164:165]
	v_and_b32_e32 v159, 64, v175
	v_pk_mov_b32 v[178:179], v[176:177], v[130:131] op_sel:[1,0]
	v_mov_b32_e32 v177, v131
	v_pk_add_f32 v[130:131], v[178:179], v[176:177]
	v_pk_mul_f32 v[176:177], v[140:141], v[140:141]
	v_pk_add_f32 v[130:131], v[130:131], v[130:131] op_sel_hi:[0,1]
	v_pk_mul_f32 v[178:179], v[142:143], v[142:143]
	v_mul_f32_e32 v130, v138, v138
	v_pk_mov_b32 v[180:181], v[178:179], v[176:177] op_sel:[1,0]
	v_mov_b32_e32 v179, v177
	v_pk_add_f32 v[176:177], v[180:181], v[178:179]
	v_pk_fma_f32 v[178:179], v[138:139], v[138:139], v[130:131] op_sel_hi:[1,1,0]
	v_mul_f32_e32 v130, v136, v136
	v_pk_add_f32 v[176:177], v[176:177], v[176:177] op_sel_hi:[0,1]
	v_pk_fma_f32 v[180:181], v[136:137], v[136:137], v[130:131] op_sel_hi:[1,1,0]
	v_mul_f32_e32 v178, v134, v134
	v_mul_f32_e32 v180, v135, v135
	v_mul_f32_e32 v130, v132, v132
	v_mul_f32_e32 v176, v133, v133
	v_pk_add_f32 v[178:179], v[178:179], v[180:181]
	v_pk_add_f32 v[130:131], v[130:131], v[176:177]
	v_add_u32_e32 v159, 64, v159
	v_pk_add_f32 v[130:131], v[178:179], v[130:131]
	s_nop 0
	v_add_f32_e32 v130, v130, v131
	v_xor_b32_e32 v131, 16, v175
	v_cmp_lt_i32_e32 vcc, v131, v159
	s_nop 1
	v_cndmask_b32_e32 v131, v175, v131, vcc
	v_lshlrev_b32_e32 v131, 2, v131
	v_mov_b32_e32 v131, v130
	s_nop 1
	v_permlane16_swap_b32_e32 v130, v131
	v_add_f32_e32 v130, v130, v131
	v_xor_b32_e32 v131, 32, v175
	v_cmp_lt_i32_e32 vcc, v131, v159
	s_nop 1
	v_cndmask_b32_e32 v131, v175, v131, vcc
	v_lshlrev_b32_e32 v131, 2, v131
	v_mov_b32_e32 v131, v130
	s_nop 1
	v_permlane32_swap_b32_e32 v130, v131
	v_add_f32_e32 v130, v130, v131
	v_fmamk_f32 v130, v130, 0x3c800000, v174
	v_rsq_f32_e32 v166, v130
.LBB0_150:
	s_and_b64 s[30:31], s[30:31], exec
	s_mov_b32 s30, 0x3200000
	s_cselect_b32 s30, s30, 0x3300000
	s_add_u32 s34, s76, s30
	s_addc_u32 s35, s77, 0
	s_lshl_b32 s30, s67, 2
	s_or_b32 s30, s30, s51
	s_ashr_i32 s31, s30, 31
	s_lshl_b64 s[30:31], s[30:31], 15
	s_add_u32 s30, s34, s30
	s_addc_u32 s31, s35, s31
	v_ashrrev_i32_e32 v159, 31, v158
	v_pk_mul_f32 v[144:145], v[144:145], v[166:167] op_sel_hi:[1,0]
	v_pk_mul_f32 v[164:165], v[164:165], v[166:167] op_sel_hi:[1,0]
	v_pk_mul_f32 v[140:141], v[140:141], v[166:167] op_sel_hi:[1,0]
	v_pk_mul_f32 v[142:143], v[142:143], v[166:167] op_sel_hi:[1,0]
	v_lshl_add_u64 v[130:131], v[162:163], 1, s[30:31]
	v_lshlrev_b64 v[162:163], 7, v[158:159]
	v_pk_mul_f32 v[144:145], v[88:89], v[144:145]
	v_pk_mul_f32 v[164:165], v[86:87], v[164:165]
	v_pk_mul_f32 v[176:177], v[84:85], v[140:141]
	v_pk_mul_f32 v[142:143], v[82:83], v[142:143]
	v_lshl_add_u64 v[162:163], v[130:131], 0, v[162:163]
	v_cvt_pk_f16_f32 v140, v164, v165
	v_cvt_pk_f16_f32 v141, v144, v145
	v_cvt_pk_f16_f32 v142, v142, v143
	v_cvt_pk_f16_f32 v143, v176, v177
	v_pk_mul_f32 v[136:137], v[136:137], v[166:167] op_sel_hi:[1,0]
	v_pk_mul_f32 v[138:139], v[138:139], v[166:167] op_sel_hi:[1,0]
	v_pk_mul_f32 v[132:133], v[132:133], v[166:167] op_sel_hi:[1,0]
	v_pk_mul_f32 v[134:135], v[134:135], v[166:167] op_sel_hi:[1,0]
	global_store_dwordx4 v[162:163], v[140:143], off
	v_pk_mul_f32 v[136:137], v[96:97], v[136:137]
	v_pk_mul_f32 v[138:139], v[94:95], v[138:139]
	v_pk_mul_f32 v[140:141], v[92:93], v[132:133]
	v_pk_mul_f32 v[134:135], v[90:91], v[134:135]
	v_cvt_pk_f16_f32 v132, v138, v139
	v_cvt_pk_f16_f32 v133, v136, v137
	v_cvt_pk_f16_f32 v134, v134, v135
	v_cvt_pk_f16_f32 v135, v140, v141
	global_store_dwordx4 v[162:163], v[132:135], off offset:64
	s_and_b64 vcc, exec, s[0:1]
	s_nop 0
	v_add_u32_e32 v132, 16, v158
	v_add_u32_e32 v134, s23, v132
	v_ashrrev_i32_e32 v135, 31, v134
	v_lshl_add_u64 v[134:135], v[134:135], 2, s[4:5]
	global_load_dword v133, v[134:135], off
	s_waitcnt vmcnt(0)
	v_fmamk_f32 v133, v133, 0x3a800000, v174
	v_rsq_f32_e32 v134, v133
	s_nop 0
	v_pk_mul_f32 v[128:129], v[128:129], v[134:135] op_sel_hi:[1,0]
	v_pk_mul_f32 v[126:127], v[126:127], v[134:135] op_sel_hi:[1,0]
	v_pk_mul_f32 v[124:125], v[124:125], v[134:135] op_sel_hi:[1,0]
	v_pk_mul_f32 v[122:123], v[122:123], v[134:135] op_sel_hi:[1,0]
	v_pk_mul_f32 v[120:121], v[120:121], v[134:135] op_sel_hi:[1,0]
	v_pk_mul_f32 v[118:119], v[118:119], v[134:135] op_sel_hi:[1,0]
	v_pk_mul_f32 v[116:117], v[116:117], v[134:135] op_sel_hi:[1,0]
	v_pk_mul_f32 v[114:115], v[114:115], v[134:135] op_sel_hi:[1,0]
	s_cbranch_vccnz .LBB0_152
; __device__ __forceinline__ unsigned pkh(float lo, float hi) { f32x2 v = {lo, hi}; h16x2 h = __builtin_convertvector(v, h16x2); return __builtin_bit_cast(unsigned, h); }
;     __device__ __forceinline__ void operator()(f32x4 (&acc)[2][2][4][2], const Unit& u, const Order& S, int wr, int wc, int fr_, int fq_, LAS unsigned char*, int) const {
;     ...
;         for (int ai = 0; ai < 2; ++ai)
; #pragma unroll
;             for (int m = 0; m < 4; ++m) {
;                 const int key = ai * HALF + wr * 64 + m * 16 + fr;
;                 const float sc = __builtin_amdgcn_rsqf(ss_in[u.pm * BM + key] * (1.0f / DM) + EPS);
;                 f32x4 v[2][2]; float sq = 0.f;
; #pragma unroll
;                 for (int bj = 0; bj < 2; ++bj)
; #pragma unroll
;                     for (int n = 0; n < 2; ++n) { v[bj][n] = acc[ai][bj][m][n] * sc; const f32x4 t = v[bj][n]; sq += (t[0] * t[0] + t[1] * t[1]) + (t[2] * t[2] + t[3] * t[3]); }
;                 float rn = 1.f;
;                 if (isk) { sq += __shfl_xor(sq, 16); sq += __shfl_xor(sq, 32); rn = __builtin_amdgcn_rsqf(sq * (1.0f / HD) + EPS); }
; #pragma unroll
;                 for (int bj = 0; bj < 2; ++bj) {
;                     const f32x4 a = v[bj][0] * rn * gv[bj][0], b = v[bj][1] * rn * gv[bj][1];
;                     u32x4 w; w.x = pkh(a[0], a[1]); w.y = pkh(a[2], a[3]); w.z = pkh(b[0], b[1]); w.w = pkh(b[2], b[3]);
;                     *(u32x4*)(dst + (size_t)key * HD + 32 * bj + 8 * fq) = w;
;                 }
	v_pk_mul_f32 v[134:135], v[128:129], v[128:129]
	v_pk_mul_f32 v[136:137], v[126:127], v[126:127]
	s_nop 0
	v_pk_mov_b32 v[138:139], v[136:137], v[134:135] op_sel:[1,0]
	v_mov_b32_e32 v137, v135
	v_pk_add_f32 v[134:135], v[138:139], v[136:137]
	v_pk_mul_f32 v[136:137], v[124:125], v[124:125]
	v_pk_add_f32 v[134:135], v[134:135], v[134:135] op_sel_hi:[0,1]
	v_pk_mul_f32 v[138:139], v[122:123], v[122:123]
	v_mul_f32_e32 v134, v118, v118
	v_pk_mov_b32 v[140:141], v[138:139], v[136:137] op_sel:[1,0]
	v_mov_b32_e32 v139, v137
	v_pk_add_f32 v[136:137], v[140:141], v[138:139]
	v_pk_fma_f32 v[138:139], v[118:119], v[118:119], v[134:135] op_sel_hi:[1,1,0]
	v_mul_f32_e32 v134, v120, v120
	v_pk_add_f32 v[136:137], v[136:137], v[136:137] op_sel_hi:[0,1]
	v_pk_fma_f32 v[140:141], v[120:121], v[120:121], v[134:135] op_sel_hi:[1,1,0]
	v_mul_f32_e32 v138, v114, v114
	v_mul_f32_e32 v140, v115, v115
	v_mul_f32_e32 v134, v116, v116
	v_mul_f32_e32 v136, v117, v117
	v_pk_add_f32 v[138:139], v[138:139], v[140:141]
	v_pk_add_f32 v[134:135], v[134:135], v[136:137]
	s_nop 0
	v_pk_add_f32 v[134:135], v[138:139], v[134:135]
	s_nop 0
	v_add_f32_e32 v133, v134, v135
	v_and_b32_e32 v135, 64, v175
	v_xor_b32_e32 v134, 16, v175
	v_add_u32_e32 v135, 64, v135
	v_cmp_lt_i32_e32 vcc, v134, v135
	s_nop 1
	v_cndmask_b32_e32 v134, v175, v134, vcc
	v_lshlrev_b32_e32 v134, 2, v134
	v_mov_b32_e32 v134, v133
	s_nop 1
	v_permlane16_swap_b32_e32 v133, v134
	v_add_f32_e32 v133, v133, v134
	v_xor_b32_e32 v134, 32, v175
	v_cmp_lt_i32_e32 vcc, v134, v135
	s_nop 1
	v_cndmask_b32_e32 v134, v175, v134, vcc
	v_lshlrev_b32_e32 v134, 2, v134
	v_mov_b32_e32 v134, v133
	s_nop 1
	v_permlane32_swap_b32_e32 v133, v134
	v_add_f32_e32 v133, v133, v134
	v_fmamk_f32 v133, v133, 0x3c800000, v174
	v_rsq_f32_e32 v160, v133
.LBB0_152:
	v_ashrrev_i32_e32 v133, 31, v132
	v_pk_mul_f32 v[128:129], v[128:129], v[160:161] op_sel_hi:[1,0]
	v_pk_mul_f32 v[126:127], v[126:127], v[160:161] op_sel_hi:[1,0]
	v_pk_mul_f32 v[124:125], v[124:125], v[160:161] op_sel_hi:[1,0]
	v_pk_mul_f32 v[122:123], v[122:123], v[160:161] op_sel_hi:[1,0]
	v_lshlrev_b64 v[132:133], 7, v[132:133]
	v_pk_mul_f32 v[128:129], v[88:89], v[128:129]
	v_pk_mul_f32 v[126:127], v[86:87], v[126:127]
	v_pk_mul_f32 v[134:135], v[84:85], v[124:125]
	v_pk_mul_f32 v[124:125], v[82:83], v[122:123]
	v_lshl_add_u64 v[132:133], v[130:131], 0, v[132:133]
	v_cvt_pk_f16_f32 v122, v126, v127
	v_cvt_pk_f16_f32 v123, v128, v129
	v_cvt_pk_f16_f32 v124, v124, v125
	v_cvt_pk_f16_f32 v125, v134, v135
	v_pk_mul_f32 v[120:121], v[120:121], v[160:161] op_sel_hi:[1,0]
	v_pk_mul_f32 v[118:119], v[118:119], v[160:161] op_sel_hi:[1,0]
	v_pk_mul_f32 v[116:117], v[116:117], v[160:161] op_sel_hi:[1,0]
	v_pk_mul_f32 v[114:115], v[114:115], v[160:161] op_sel_hi:[1,0]
	global_store_dwordx4 v[132:133], v[122:125], off
	v_pk_mul_f32 v[120:121], v[96:97], v[120:121]
	v_pk_mul_f32 v[118:119], v[94:95], v[118:119]
	v_pk_mul_f32 v[122:123], v[92:93], v[116:117]
	v_pk_mul_f32 v[116:117], v[90:91], v[114:115]
	v_cvt_pk_f16_f32 v114, v118, v119
	v_cvt_pk_f16_f32 v115, v120, v121
	v_cvt_pk_f16_f32 v116, v116, v117
	v_cvt_pk_f16_f32 v117, v122, v123
	global_store_dwordx4 v[132:133], v[114:117], off offset:64
	s_and_b64 vcc, exec, s[0:1]
	s_nop 0
	v_add_u32_e32 v116, 32, v158
	v_add_u32_e32 v114, s23, v116
	v_ashrrev_i32_e32 v115, 31, v114
	v_lshl_add_u64 v[114:115], v[114:115], 2, s[4:5]
	global_load_dword v114, v[114:115], off
	s_waitcnt vmcnt(0)
	v_fmamk_f32 v114, v114, 0x3a800000, v174
	v_rsq_f32_e32 v118, v114
	v_mov_b32_e32 v114, 1.0
	v_pk_mul_f32 v[112:113], v[112:113], v[118:119] op_sel_hi:[1,0]
	v_pk_mul_f32 v[110:111], v[110:111], v[118:119] op_sel_hi:[1,0]
	v_pk_mul_f32 v[108:109], v[108:109], v[118:119] op_sel_hi:[1,0]
	v_pk_mul_f32 v[106:107], v[106:107], v[118:119] op_sel_hi:[1,0]
	v_pk_mul_f32 v[104:105], v[104:105], v[118:119] op_sel_hi:[1,0]
	v_pk_mul_f32 v[102:103], v[102:103], v[118:119] op_sel_hi:[1,0]
	v_pk_mul_f32 v[100:101], v[100:101], v[118:119] op_sel_hi:[1,0]
	v_pk_mul_f32 v[98:99], v[98:99], v[118:119] op_sel_hi:[1,0]
	v_mov_b32_e32 v118, 1.0
	s_cbranch_vccnz .LBB0_154
	v_pk_mul_f32 v[118:119], v[112:113], v[112:113]
	v_pk_mul_f32 v[120:121], v[110:111], v[110:111]
	v_xor_b32_e32 v117, 16, v175
	v_pk_mov_b32 v[122:123], v[120:121], v[118:119] op_sel:[1,0]
	v_mov_b32_e32 v121, v119
	v_pk_add_f32 v[118:119], v[122:123], v[120:121]
	v_pk_mul_f32 v[120:121], v[108:109], v[108:109]
	v_pk_add_f32 v[118:119], v[118:119], v[118:119] op_sel_hi:[0,1]
	v_pk_mul_f32 v[122:123], v[106:107], v[106:107]
	v_mul_f32_e32 v118, v102, v102
	v_pk_mov_b32 v[124:125], v[122:123], v[120:121] op_sel:[1,0]
	v_mov_b32_e32 v123, v121
	v_pk_add_f32 v[120:121], v[124:125], v[122:123]
	v_pk_fma_f32 v[122:123], v[102:103], v[102:103], v[118:119] op_sel_hi:[1,1,0]
	v_mul_f32_e32 v118, v104, v104
	v_pk_add_f32 v[120:121], v[120:121], v[120:121] op_sel_hi:[0,1]
	v_pk_fma_f32 v[124:125], v[104:105], v[104:105], v[118:119] op_sel_hi:[1,1,0]
	v_mul_f32_e32 v122, v98, v98
	v_mul_f32_e32 v124, v99, v99
	v_mul_f32_e32 v118, v100, v100
	v_mul_f32_e32 v120, v101, v101
	v_pk_add_f32 v[122:123], v[122:123], v[124:125]
	v_pk_add_f32 v[118:119], v[118:119], v[120:121]
	s_nop 0
	v_pk_add_f32 v[118:119], v[122:123], v[118:119]
	s_nop 0
	v_add_f32_e32 v115, v118, v119
	v_and_b32_e32 v118, 64, v175
	v_add_u32_e32 v118, 64, v118
	v_cmp_lt_i32_e32 vcc, v117, v118
	s_nop 1
	v_cndmask_b32_e32 v117, v175, v117, vcc
	v_lshlrev_b32_e32 v117, 2, v117
	v_mov_b32_e32 v117, v115
	s_nop 1
	v_permlane16_swap_b32_e32 v115, v117
	v_add_f32_e32 v115, v115, v117
	v_xor_b32_e32 v117, 32, v175
	v_cmp_lt_i32_e32 vcc, v117, v118
	s_nop 1
	v_cndmask_b32_e32 v117, v175, v117, vcc
	v_lshlrev_b32_e32 v117, 2, v117
	v_mov_b32_e32 v117, v115
	s_nop 1
	v_permlane32_swap_b32_e32 v115, v117
	v_add_f32_e32 v115, v115, v117
	v_fmamk_f32 v115, v115, 0x3c800000, v174
	v_rsq_f32_e32 v118, v115
; __device__ __forceinline__ unsigned pkh(float lo, float hi) { f32x2 v = {lo, hi}; h16x2 h = __builtin_convertvector(v, h16x2); return __builtin_bit_cast(unsigned, h); }
;     __device__ __forceinline__ void operator()(f32x4 (&acc)[2][2][4][2], const Unit& u, const Order& S, int wr, int wc, int fr_, int fq_, LAS unsigned char*, int) const {
;     ...
;         for (int ai = 0; ai < 2; ++ai)
; #pragma unroll
;             for (int m = 0; m < 4; ++m) {
;                 const int key = ai * HALF + wr * 64 + m * 16 + fr;
;                 const float sc = __builtin_amdgcn_rsqf(ss_in[u.pm * BM + key] * (1.0f / DM) + EPS);
;                 f32x4 v[2][2]; float sq = 0.f;
; #pragma unroll
;                 for (int bj = 0; bj < 2; ++bj)
; #pragma unroll
;                     for (int n = 0; n < 2; ++n) { v[bj][n] = acc[ai][bj][m][n] * sc; const f32x4 t = v[bj][n]; sq += (t[0] * t[0] + t[1] * t[1]) + (t[2] * t[2] + t[3] * t[3]); }
;                 float rn = 1.f;
;                 if (isk) { sq += __shfl_xor(sq, 16); sq += __shfl_xor(sq, 32); rn = __builtin_amdgcn_rsqf(sq * (1.0f / HD) + EPS); }
; #pragma unroll
;                 for (int bj = 0; bj < 2; ++bj) {
;                     const f32x4 a = v[bj][0] * rn * gv[bj][0], b = v[bj][1] * rn * gv[bj][1];
;                     u32x4 w; w.x = pkh(a[0], a[1]); w.y = pkh(a[2], a[3]); w.z = pkh(b[0], b[1]); w.w = pkh(b[2], b[3]);
;                     *(u32x4*)(dst + (size_t)key * HD + 32 * bj + 8 * fq) = w;
;                 }
.LBB0_154:
	v_ashrrev_i32_e32 v117, 31, v116
	v_pk_mul_f32 v[112:113], v[112:113], v[118:119] op_sel_hi:[1,0]
	v_pk_mul_f32 v[110:111], v[110:111], v[118:119] op_sel_hi:[1,0]
	v_pk_mul_f32 v[108:109], v[108:109], v[118:119] op_sel_hi:[1,0]
	v_pk_mul_f32 v[106:107], v[106:107], v[118:119] op_sel_hi:[1,0]
	v_lshlrev_b64 v[116:117], 7, v[116:117]
	v_pk_mul_f32 v[112:113], v[88:89], v[112:113]
	v_pk_mul_f32 v[110:111], v[86:87], v[110:111]
	v_pk_mul_f32 v[120:121], v[84:85], v[108:109]
	v_pk_mul_f32 v[108:109], v[82:83], v[106:107]
	v_lshl_add_u64 v[116:117], v[130:131], 0, v[116:117]
	v_cvt_pk_f16_f32 v106, v110, v111
	v_cvt_pk_f16_f32 v107, v112, v113
	v_cvt_pk_f16_f32 v108, v108, v109
	v_cvt_pk_f16_f32 v109, v120, v121
	v_pk_mul_f32 v[104:105], v[104:105], v[118:119] op_sel_hi:[1,0]
	v_pk_mul_f32 v[102:103], v[102:103], v[118:119] op_sel_hi:[1,0]
	v_pk_mul_f32 v[100:101], v[100:101], v[118:119] op_sel_hi:[1,0]
	v_pk_mul_f32 v[98:99], v[98:99], v[118:119] op_sel_hi:[1,0]
	global_store_dwordx4 v[116:117], v[106:109], off
	v_pk_mul_f32 v[104:105], v[96:97], v[104:105]
	v_pk_mul_f32 v[102:103], v[94:95], v[102:103]
	v_pk_mul_f32 v[106:107], v[92:93], v[100:101]
	v_pk_mul_f32 v[100:101], v[90:91], v[98:99]
	v_cvt_pk_f16_f32 v98, v102, v103
	v_cvt_pk_f16_f32 v99, v104, v105
	v_cvt_pk_f16_f32 v100, v100, v101
	v_cvt_pk_f16_f32 v101, v106, v107
	global_store_dwordx4 v[116:117], v[98:101], off offset:64
	s_and_b64 vcc, exec, s[0:1]
	s_nop 0
	v_add_u32_e32 v98, 48, v158
	v_add_u32_e32 v100, s23, v98
	v_ashrrev_i32_e32 v101, 31, v100
	v_lshl_add_u64 v[100:101], v[100:101], 2, s[4:5]
	global_load_dword v99, v[100:101], off
	s_waitcnt vmcnt(0)
	v_fmamk_f32 v99, v99, 0x3a800000, v174
	v_rsq_f32_e32 v100, v99
	s_nop 0
	v_pk_mul_f32 v[80:81], v[80:81], v[100:101] op_sel_hi:[1,0]
	v_pk_mul_f32 v[78:79], v[78:79], v[100:101] op_sel_hi:[1,0]
	v_pk_mul_f32 v[76:77], v[76:77], v[100:101] op_sel_hi:[1,0]
	v_pk_mul_f32 v[74:75], v[74:75], v[100:101] op_sel_hi:[1,0]
	v_pk_mul_f32 v[72:73], v[72:73], v[100:101] op_sel_hi:[1,0]
	v_pk_mul_f32 v[70:71], v[70:71], v[100:101] op_sel_hi:[1,0]
	v_pk_mul_f32 v[68:69], v[68:69], v[100:101] op_sel_hi:[1,0]
	v_pk_mul_f32 v[66:67], v[66:67], v[100:101] op_sel_hi:[1,0]
	s_cbranch_vccnz .LBB0_156
	v_pk_mul_f32 v[100:101], v[80:81], v[80:81]
	v_pk_mul_f32 v[102:103], v[78:79], v[78:79]
	s_nop 0
	v_pk_mov_b32 v[104:105], v[102:103], v[100:101] op_sel:[1,0]
	v_mov_b32_e32 v103, v101
	v_pk_add_f32 v[100:101], v[104:105], v[102:103]
	v_pk_mul_f32 v[102:103], v[76:77], v[76:77]
	v_pk_add_f32 v[100:101], v[100:101], v[100:101] op_sel_hi:[0,1]
	v_pk_mul_f32 v[104:105], v[74:75], v[74:75]
	v_mul_f32_e32 v100, v70, v70
	v_pk_mov_b32 v[106:107], v[104:105], v[102:103] op_sel:[1,0]
	v_mov_b32_e32 v105, v103
	v_pk_add_f32 v[102:103], v[106:107], v[104:105]
	v_pk_fma_f32 v[104:105], v[70:71], v[70:71], v[100:101] op_sel_hi:[1,1,0]
	v_mul_f32_e32 v100, v72, v72
	v_pk_add_f32 v[102:103], v[102:103], v[102:103] op_sel_hi:[0,1]
	v_pk_fma_f32 v[106:107], v[72:73], v[72:73], v[100:101] op_sel_hi:[1,1,0]
	v_mul_f32_e32 v104, v66, v66
	v_mul_f32_e32 v106, v67, v67
	v_mul_f32_e32 v100, v68, v68
	v_mul_f32_e32 v102, v69, v69
	v_pk_add_f32 v[104:105], v[104:105], v[106:107]
	v_pk_add_f32 v[100:101], v[100:101], v[102:103]
	s_nop 0
	v_pk_add_f32 v[100:101], v[104:105], v[100:101]
	s_nop 0
	v_add_f32_e32 v99, v100, v101
	v_and_b32_e32 v101, 64, v175
	v_xor_b32_e32 v100, 16, v175
	v_add_u32_e32 v101, 64, v101
	v_cmp_lt_i32_e32 vcc, v100, v101
	s_nop 1
	v_cndmask_b32_e32 v100, v175, v100, vcc
	v_lshlrev_b32_e32 v100, 2, v100
	v_mov_b32_e32 v100, v99
	s_nop 1
	v_permlane16_swap_b32_e32 v99, v100
	v_add_f32_e32 v99, v99, v100
	v_xor_b32_e32 v100, 32, v175
	v_cmp_lt_i32_e32 vcc, v100, v101
	s_nop 1
	v_cndmask_b32_e32 v100, v175, v100, vcc
	v_lshlrev_b32_e32 v100, 2, v100
	v_mov_b32_e32 v100, v99
	s_nop 1
	v_permlane32_swap_b32_e32 v99, v100
	v_add_f32_e32 v99, v99, v100
	v_fmamk_f32 v99, v99, 0x3c800000, v174
	v_rsq_f32_e32 v114, v99
.LBB0_156:
	v_ashrrev_i32_e32 v99, 31, v98
	v_pk_mul_f32 v[80:81], v[80:81], v[114:115] op_sel_hi:[1,0]
	v_pk_mul_f32 v[78:79], v[78:79], v[114:115] op_sel_hi:[1,0]
	v_pk_mul_f32 v[76:77], v[76:77], v[114:115] op_sel_hi:[1,0]
	v_pk_mul_f32 v[74:75], v[74:75], v[114:115] op_sel_hi:[1,0]
	v_lshlrev_b64 v[98:99], 7, v[98:99]
	v_pk_mul_f32 v[80:81], v[88:89], v[80:81]
	v_pk_mul_f32 v[78:79], v[86:87], v[78:79]
	v_pk_mul_f32 v[100:101], v[84:85], v[76:77]
	v_pk_mul_f32 v[76:77], v[82:83], v[74:75]
	v_lshl_add_u64 v[98:99], v[130:131], 0, v[98:99]
	v_cvt_pk_f16_f32 v74, v78, v79
	v_cvt_pk_f16_f32 v75, v80, v81
	v_cvt_pk_f16_f32 v76, v76, v77
	v_cvt_pk_f16_f32 v77, v100, v101
	v_pk_mul_f32 v[72:73], v[72:73], v[114:115] op_sel_hi:[1,0]
	v_pk_mul_f32 v[70:71], v[70:71], v[114:115] op_sel_hi:[1,0]
	v_pk_mul_f32 v[68:69], v[68:69], v[114:115] op_sel_hi:[1,0]
	v_pk_mul_f32 v[66:67], v[66:67], v[114:115] op_sel_hi:[1,0]
	global_store_dwordx4 v[98:99], v[74:77], off
	v_pk_mul_f32 v[72:73], v[96:97], v[72:73]
	v_pk_mul_f32 v[70:71], v[94:95], v[70:71]
	v_pk_mul_f32 v[74:75], v[92:93], v[68:69]
	v_pk_mul_f32 v[68:69], v[90:91], v[66:67]
	v_cvt_pk_f16_f32 v66, v70, v71
	v_cvt_pk_f16_f32 v67, v72, v73
	v_cvt_pk_f16_f32 v68, v68, v69
	v_cvt_pk_f16_f32 v69, v74, v75
	global_store_dwordx4 v[98:99], v[66:69], off offset:64
	s_and_b64 vcc, exec, s[0:1]
	s_nop 0
	v_add_u32_e32 v68, 0x80, v158
	v_add_u32_e32 v66, s23, v68
	v_ashrrev_i32_e32 v67, 31, v66
	v_lshl_add_u64 v[66:67], v[66:67], 2, s[4:5]
	global_load_dword v66, v[66:67], off
	s_waitcnt vmcnt(0)
	v_fmamk_f32 v66, v66, 0x3a800000, v174
	v_rsq_f32_e32 v70, v66
	v_mov_b32_e32 v66, 1.0
	v_pk_mul_f32 v[64:65], v[64:65], v[70:71] op_sel_hi:[1,0]
	v_pk_mul_f32 v[62:63], v[62:63], v[70:71] op_sel_hi:[1,0]
	v_pk_mul_f32 v[60:61], v[60:61], v[70:71] op_sel_hi:[1,0]
	v_pk_mul_f32 v[58:59], v[58:59], v[70:71] op_sel_hi:[1,0]
	v_pk_mul_f32 v[56:57], v[56:57], v[70:71] op_sel_hi:[1,0]
	v_pk_mul_f32 v[54:55], v[54:55], v[70:71] op_sel_hi:[1,0]
	v_pk_mul_f32 v[52:53], v[52:53], v[70:71] op_sel_hi:[1,0]
	v_pk_mul_f32 v[50:51], v[50:51], v[70:71] op_sel_hi:[1,0]
	v_mov_b32_e32 v70, 1.0
	s_cbranch_vccnz .LBB0_158
; __device__ __forceinline__ unsigned pkh(float lo, float hi) { f32x2 v = {lo, hi}; h16x2 h = __builtin_convertvector(v, h16x2); return __builtin_bit_cast(unsigned, h); }
;     __device__ __forceinline__ void operator()(f32x4 (&acc)[2][2][4][2], const Unit& u, const Order& S, int wr, int wc, int fr_, int fq_, LAS unsigned char*, int) const {
;     ...
;         for (int ai = 0; ai < 2; ++ai)
; #pragma unroll
;             for (int m = 0; m < 4; ++m) {
;                 const int key = ai * HALF + wr * 64 + m * 16 + fr;
;                 const float sc = __builtin_amdgcn_rsqf(ss_in[u.pm * BM + key] * (1.0f / DM) + EPS);
;                 f32x4 v[2][2]; float sq = 0.f;
; #pragma unroll
;                 for (int bj = 0; bj < 2; ++bj)
; #pragma unroll
;                     for (int n = 0; n < 2; ++n) { v[bj][n] = acc[ai][bj][m][n] * sc; const f32x4 t = v[bj][n]; sq += (t[0] * t[0] + t[1] * t[1]) + (t[2] * t[2] + t[3] * t[3]); }
;                 float rn = 1.f;
;                 if (isk) { sq += __shfl_xor(sq, 16); sq += __shfl_xor(sq, 32); rn = __builtin_amdgcn_rsqf(sq * (1.0f / HD) + EPS); }
; #pragma unroll
;                 for (int bj = 0; bj < 2; ++bj) {
;                     const f32x4 a = v[bj][0] * rn * gv[bj][0], b = v[bj][1] * rn * gv[bj][1];
;                     u32x4 w; w.x = pkh(a[0], a[1]); w.y = pkh(a[2], a[3]); w.z = pkh(b[0], b[1]); w.w = pkh(b[2], b[3]);
;                     *(u32x4*)(dst + (size_t)key * HD + 32 * bj + 8 * fq) = w;
;                 }
	v_pk_mul_f32 v[70:71], v[64:65], v[64:65]
	v_pk_mul_f32 v[72:73], v[62:63], v[62:63]
	v_xor_b32_e32 v69, 16, v175
	v_pk_mov_b32 v[74:75], v[72:73], v[70:71] op_sel:[1,0]
	v_mov_b32_e32 v73, v71
	v_pk_add_f32 v[70:71], v[74:75], v[72:73]
	v_pk_mul_f32 v[72:73], v[60:61], v[60:61]
	v_pk_add_f32 v[70:71], v[70:71], v[70:71] op_sel_hi:[0,1]
	v_pk_mul_f32 v[74:75], v[58:59], v[58:59]
	v_mul_f32_e32 v70, v54, v54
	v_pk_mov_b32 v[76:77], v[74:75], v[72:73] op_sel:[1,0]
	v_mov_b32_e32 v75, v73
	v_pk_add_f32 v[72:73], v[76:77], v[74:75]
	v_pk_fma_f32 v[74:75], v[54:55], v[54:55], v[70:71] op_sel_hi:[1,1,0]
	v_mul_f32_e32 v70, v56, v56
	v_pk_add_f32 v[72:73], v[72:73], v[72:73] op_sel_hi:[0,1]
	v_pk_fma_f32 v[76:77], v[56:57], v[56:57], v[70:71] op_sel_hi:[1,1,0]
	v_mul_f32_e32 v74, v50, v50
	v_mul_f32_e32 v76, v51, v51
	v_mul_f32_e32 v70, v52, v52
	v_mul_f32_e32 v72, v53, v53
	v_pk_add_f32 v[74:75], v[74:75], v[76:77]
	v_pk_add_f32 v[70:71], v[70:71], v[72:73]
	s_nop 0
	v_pk_add_f32 v[70:71], v[74:75], v[70:71]
	s_nop 0
	v_add_f32_e32 v67, v70, v71
	v_and_b32_e32 v70, 64, v175
	v_add_u32_e32 v70, 64, v70
	v_cmp_lt_i32_e32 vcc, v69, v70
	s_nop 1
	v_cndmask_b32_e32 v69, v175, v69, vcc
	v_lshlrev_b32_e32 v69, 2, v69
	v_mov_b32_e32 v69, v67
	s_nop 1
	v_permlane16_swap_b32_e32 v67, v69
	v_add_f32_e32 v67, v67, v69
	v_xor_b32_e32 v69, 32, v175
	v_cmp_lt_i32_e32 vcc, v69, v70
	s_nop 1
	v_cndmask_b32_e32 v69, v175, v69, vcc
	v_lshlrev_b32_e32 v69, 2, v69
	v_mov_b32_e32 v69, v67
	s_nop 1
	v_permlane32_swap_b32_e32 v67, v69
	v_add_f32_e32 v67, v67, v69
	v_fmamk_f32 v67, v67, 0x3c800000, v174
	v_rsq_f32_e32 v70, v67
.LBB0_158:
	v_ashrrev_i32_e32 v69, 31, v68
	v_pk_mul_f32 v[64:65], v[64:65], v[70:71] op_sel_hi:[1,0]
	v_pk_mul_f32 v[62:63], v[62:63], v[70:71] op_sel_hi:[1,0]
	v_pk_mul_f32 v[60:61], v[60:61], v[70:71] op_sel_hi:[1,0]
	v_pk_mul_f32 v[58:59], v[58:59], v[70:71] op_sel_hi:[1,0]
	v_lshlrev_b64 v[68:69], 7, v[68:69]
	v_pk_mul_f32 v[64:65], v[88:89], v[64:65]
	v_pk_mul_f32 v[62:63], v[86:87], v[62:63]
	v_pk_mul_f32 v[72:73], v[84:85], v[60:61]
	v_pk_mul_f32 v[60:61], v[82:83], v[58:59]
	v_lshl_add_u64 v[68:69], v[130:131], 0, v[68:69]
	v_cvt_pk_f16_f32 v58, v62, v63
	v_cvt_pk_f16_f32 v59, v64, v65
	v_cvt_pk_f16_f32 v60, v60, v61
	v_cvt_pk_f16_f32 v61, v72, v73
	v_pk_mul_f32 v[56:57], v[56:57], v[70:71] op_sel_hi:[1,0]
	v_pk_mul_f32 v[54:55], v[54:55], v[70:71] op_sel_hi:[1,0]
	v_pk_mul_f32 v[52:53], v[52:53], v[70:71] op_sel_hi:[1,0]
	v_pk_mul_f32 v[50:51], v[50:51], v[70:71] op_sel_hi:[1,0]
	global_store_dwordx4 v[68:69], v[58:61], off
	v_pk_mul_f32 v[56:57], v[96:97], v[56:57]
	v_pk_mul_f32 v[54:55], v[94:95], v[54:55]
	v_pk_mul_f32 v[58:59], v[92:93], v[52:53]
	v_pk_mul_f32 v[52:53], v[90:91], v[50:51]
	v_cvt_pk_f16_f32 v50, v54, v55
	v_cvt_pk_f16_f32 v51, v56, v57
	v_cvt_pk_f16_f32 v52, v52, v53
	v_cvt_pk_f16_f32 v53, v58, v59
	global_store_dwordx4 v[68:69], v[50:53], off offset:64
	s_and_b64 vcc, exec, s[0:1]
	s_nop 0
	v_add_u32_e32 v50, 0x90, v158
	v_add_u32_e32 v52, s23, v50
	v_ashrrev_i32_e32 v53, 31, v52
	v_lshl_add_u64 v[52:53], v[52:53], 2, s[4:5]
	global_load_dword v51, v[52:53], off
	s_waitcnt vmcnt(0)
	v_fmamk_f32 v51, v51, 0x3a800000, v174
	v_rsq_f32_e32 v52, v51
	s_nop 0
	v_pk_mul_f32 v[48:49], v[48:49], v[52:53] op_sel_hi:[1,0]
	v_pk_mul_f32 v[46:47], v[46:47], v[52:53] op_sel_hi:[1,0]
	v_pk_mul_f32 v[44:45], v[44:45], v[52:53] op_sel_hi:[1,0]
	v_pk_mul_f32 v[42:43], v[42:43], v[52:53] op_sel_hi:[1,0]
	v_pk_mul_f32 v[40:41], v[40:41], v[52:53] op_sel_hi:[1,0]
	v_pk_mul_f32 v[38:39], v[38:39], v[52:53] op_sel_hi:[1,0]
	v_pk_mul_f32 v[36:37], v[36:37], v[52:53] op_sel_hi:[1,0]
	v_pk_mul_f32 v[34:35], v[34:35], v[52:53] op_sel_hi:[1,0]
	s_cbranch_vccnz .LBB0_160
	v_pk_mul_f32 v[52:53], v[48:49], v[48:49]
	v_pk_mul_f32 v[54:55], v[46:47], v[46:47]
	s_nop 0
	v_pk_mov_b32 v[56:57], v[54:55], v[52:53] op_sel:[1,0]
	v_mov_b32_e32 v55, v53
	v_pk_add_f32 v[52:53], v[56:57], v[54:55]
	v_pk_mul_f32 v[54:55], v[44:45], v[44:45]
	v_pk_add_f32 v[52:53], v[52:53], v[52:53] op_sel_hi:[0,1]
	v_pk_mul_f32 v[56:57], v[42:43], v[42:43]
	v_mul_f32_e32 v52, v38, v38
	v_pk_mov_b32 v[58:59], v[56:57], v[54:55] op_sel:[1,0]
	v_mov_b32_e32 v57, v55
	v_pk_add_f32 v[54:55], v[58:59], v[56:57]
	v_pk_fma_f32 v[56:57], v[38:39], v[38:39], v[52:53] op_sel_hi:[1,1,0]
	v_mul_f32_e32 v52, v40, v40
	v_pk_add_f32 v[54:55], v[54:55], v[54:55] op_sel_hi:[0,1]
	v_pk_fma_f32 v[58:59], v[40:41], v[40:41], v[52:53] op_sel_hi:[1,1,0]
	v_mul_f32_e32 v56, v34, v34
	v_mul_f32_e32 v58, v35, v35
	v_mul_f32_e32 v52, v36, v36
	v_mul_f32_e32 v54, v37, v37
	v_pk_add_f32 v[56:57], v[56:57], v[58:59]
	v_pk_add_f32 v[52:53], v[52:53], v[54:55]
	s_nop 0
	v_pk_add_f32 v[52:53], v[56:57], v[52:53]
	s_nop 0
	v_add_f32_e32 v51, v52, v53
	v_and_b32_e32 v53, 64, v175
	v_xor_b32_e32 v52, 16, v175
	v_add_u32_e32 v53, 64, v53
	v_cmp_lt_i32_e32 vcc, v52, v53
	s_nop 1
	v_cndmask_b32_e32 v52, v175, v52, vcc
	v_lshlrev_b32_e32 v52, 2, v52
	v_mov_b32_e32 v52, v51
	s_nop 1
	v_permlane16_swap_b32_e32 v51, v52
	v_add_f32_e32 v51, v51, v52
	v_xor_b32_e32 v52, 32, v175
	v_cmp_lt_i32_e32 vcc, v52, v53
	s_nop 1
	v_cndmask_b32_e32 v52, v175, v52, vcc
	v_lshlrev_b32_e32 v52, 2, v52
	v_mov_b32_e32 v52, v51
	s_nop 1
	v_permlane32_swap_b32_e32 v51, v52
	v_add_f32_e32 v51, v51, v52
	v_fmamk_f32 v51, v51, 0x3c800000, v174
	v_rsq_f32_e32 v66, v51
; __device__ __forceinline__ unsigned pkh(float lo, float hi) { f32x2 v = {lo, hi}; h16x2 h = __builtin_convertvector(v, h16x2); return __builtin_bit_cast(unsigned, h); }
;     __device__ __forceinline__ void operator()(f32x4 (&acc)[2][2][4][2], const Unit& u, const Order& S, int wr, int wc, int fr_, int fq_, LAS unsigned char*, int) const {
;     ...
;         for (int ai = 0; ai < 2; ++ai)
; #pragma unroll
;             for (int m = 0; m < 4; ++m) {
;                 const int key = ai * HALF + wr * 64 + m * 16 + fr;
;                 const float sc = __builtin_amdgcn_rsqf(ss_in[u.pm * BM + key] * (1.0f / DM) + EPS);
;                 f32x4 v[2][2]; float sq = 0.f;
; #pragma unroll
;                 for (int bj = 0; bj < 2; ++bj)
; #pragma unroll
;                     for (int n = 0; n < 2; ++n) { v[bj][n] = acc[ai][bj][m][n] * sc; const f32x4 t = v[bj][n]; sq += (t[0] * t[0] + t[1] * t[1]) + (t[2] * t[2] + t[3] * t[3]); }
;                 float rn = 1.f;
;                 if (isk) { sq += __shfl_xor(sq, 16); sq += __shfl_xor(sq, 32); rn = __builtin_amdgcn_rsqf(sq * (1.0f / HD) + EPS); }
; #pragma unroll
;                 for (int bj = 0; bj < 2; ++bj) {
;                     const f32x4 a = v[bj][0] * rn * gv[bj][0], b = v[bj][1] * rn * gv[bj][1];
;                     u32x4 w; w.x = pkh(a[0], a[1]); w.y = pkh(a[2], a[3]); w.z = pkh(b[0], b[1]); w.w = pkh(b[2], b[3]);
;                     *(u32x4*)(dst + (size_t)key * HD + 32 * bj + 8 * fq) = w;
;                 }
.LBB0_160:
	v_ashrrev_i32_e32 v51, 31, v50
	v_pk_mul_f32 v[48:49], v[48:49], v[66:67] op_sel_hi:[1,0]
	v_pk_mul_f32 v[46:47], v[46:47], v[66:67] op_sel_hi:[1,0]
	v_pk_mul_f32 v[44:45], v[44:45], v[66:67] op_sel_hi:[1,0]
	v_pk_mul_f32 v[42:43], v[42:43], v[66:67] op_sel_hi:[1,0]
	v_lshlrev_b64 v[50:51], 7, v[50:51]
	v_pk_mul_f32 v[48:49], v[88:89], v[48:49]
	v_pk_mul_f32 v[46:47], v[86:87], v[46:47]
	v_pk_mul_f32 v[52:53], v[84:85], v[44:45]
	v_pk_mul_f32 v[44:45], v[82:83], v[42:43]
	v_lshl_add_u64 v[50:51], v[130:131], 0, v[50:51]
	v_cvt_pk_f16_f32 v42, v46, v47
	v_cvt_pk_f16_f32 v43, v48, v49
	v_cvt_pk_f16_f32 v44, v44, v45
	v_cvt_pk_f16_f32 v45, v52, v53
	v_pk_mul_f32 v[40:41], v[40:41], v[66:67] op_sel_hi:[1,0]
	v_pk_mul_f32 v[38:39], v[38:39], v[66:67] op_sel_hi:[1,0]
	v_pk_mul_f32 v[36:37], v[36:37], v[66:67] op_sel_hi:[1,0]
	v_pk_mul_f32 v[34:35], v[34:35], v[66:67] op_sel_hi:[1,0]
	global_store_dwordx4 v[50:51], v[42:45], off
	v_pk_mul_f32 v[40:41], v[96:97], v[40:41]
	v_pk_mul_f32 v[38:39], v[94:95], v[38:39]
	v_pk_mul_f32 v[42:43], v[92:93], v[36:37]
	v_pk_mul_f32 v[36:37], v[90:91], v[34:35]
	v_cvt_pk_f16_f32 v34, v38, v39
	v_cvt_pk_f16_f32 v35, v40, v41
	v_cvt_pk_f16_f32 v36, v36, v37
	v_cvt_pk_f16_f32 v37, v42, v43
	global_store_dwordx4 v[50:51], v[34:37], off offset:64
	s_and_b64 vcc, exec, s[0:1]
	s_nop 0
	v_add_u32_e32 v36, 0xa0, v158
	v_add_u32_e32 v34, s23, v36
	v_ashrrev_i32_e32 v35, 31, v34
	v_lshl_add_u64 v[34:35], v[34:35], 2, s[4:5]
	global_load_dword v34, v[34:35], off
	s_waitcnt vmcnt(0)
	v_fmamk_f32 v34, v34, 0x3a800000, v174
	v_rsq_f32_e32 v38, v34
	v_mov_b32_e32 v34, 1.0
	v_pk_mul_f32 v[32:33], v[32:33], v[38:39] op_sel_hi:[1,0]
	v_pk_mul_f32 v[30:31], v[30:31], v[38:39] op_sel_hi:[1,0]
	v_pk_mul_f32 v[28:29], v[28:29], v[38:39] op_sel_hi:[1,0]
	v_pk_mul_f32 v[26:27], v[26:27], v[38:39] op_sel_hi:[1,0]
	v_pk_mul_f32 v[24:25], v[24:25], v[38:39] op_sel_hi:[1,0]
	v_pk_mul_f32 v[22:23], v[22:23], v[38:39] op_sel_hi:[1,0]
	v_pk_mul_f32 v[20:21], v[20:21], v[38:39] op_sel_hi:[1,0]
	v_pk_mul_f32 v[18:19], v[18:19], v[38:39] op_sel_hi:[1,0]
	v_mov_b32_e32 v38, 1.0
	s_cbranch_vccnz .LBB0_162
	v_pk_mul_f32 v[38:39], v[32:33], v[32:33]
	v_pk_mul_f32 v[40:41], v[30:31], v[30:31]
	v_xor_b32_e32 v37, 16, v175
	v_pk_mov_b32 v[42:43], v[40:41], v[38:39] op_sel:[1,0]
	v_mov_b32_e32 v41, v39
	v_pk_add_f32 v[38:39], v[42:43], v[40:41]
	v_pk_mul_f32 v[40:41], v[28:29], v[28:29]
	v_pk_add_f32 v[38:39], v[38:39], v[38:39] op_sel_hi:[0,1]
	v_pk_mul_f32 v[42:43], v[26:27], v[26:27]
	v_mul_f32_e32 v38, v22, v22
	v_pk_mov_b32 v[44:45], v[42:43], v[40:41] op_sel:[1,0]
	v_mov_b32_e32 v43, v41
	v_pk_add_f32 v[40:41], v[44:45], v[42:43]
	v_pk_fma_f32 v[42:43], v[22:23], v[22:23], v[38:39] op_sel_hi:[1,1,0]
	v_mul_f32_e32 v38, v24, v24
	v_pk_add_f32 v[40:41], v[40:41], v[40:41] op_sel_hi:[0,1]
	v_pk_fma_f32 v[44:45], v[24:25], v[24:25], v[38:39] op_sel_hi:[1,1,0]
	v_mul_f32_e32 v42, v18, v18
	v_mul_f32_e32 v44, v19, v19
	v_mul_f32_e32 v38, v20, v20
	v_mul_f32_e32 v40, v21, v21
	v_pk_add_f32 v[42:43], v[42:43], v[44:45]
	v_pk_add_f32 v[38:39], v[38:39], v[40:41]
	s_nop 0
	v_pk_add_f32 v[38:39], v[42:43], v[38:39]
	s_nop 0
	v_add_f32_e32 v35, v38, v39
	v_and_b32_e32 v38, 64, v175
	v_add_u32_e32 v38, 64, v38
	v_cmp_lt_i32_e32 vcc, v37, v38
	s_nop 1
	v_cndmask_b32_e32 v37, v175, v37, vcc
	v_lshlrev_b32_e32 v37, 2, v37
	v_mov_b32_e32 v37, v35
	s_nop 1
	v_permlane16_swap_b32_e32 v35, v37
	v_add_f32_e32 v35, v35, v37
	v_xor_b32_e32 v37, 32, v175
	v_cmp_lt_i32_e32 vcc, v37, v38
	s_nop 1
	v_cndmask_b32_e32 v37, v175, v37, vcc
	v_lshlrev_b32_e32 v37, 2, v37
	v_mov_b32_e32 v37, v35
	s_nop 1
	v_permlane32_swap_b32_e32 v35, v37
	v_add_f32_e32 v35, v35, v37
	v_fmamk_f32 v35, v35, 0x3c800000, v174
	v_rsq_f32_e32 v38, v35
; __device__ __forceinline__ unsigned pkh(float lo, float hi) { f32x2 v = {lo, hi}; h16x2 h = __builtin_convertvector(v, h16x2); return __builtin_bit_cast(unsigned, h); }
;     __device__ __forceinline__ void operator()(f32x4 (&acc)[2][2][4][2], const Unit& u, const Order& S, int wr, int wc, int fr_, int fq_, LAS unsigned char*, int) const {
;     ...
;         for (int ai = 0; ai < 2; ++ai)
; #pragma unroll
;             for (int m = 0; m < 4; ++m) {
;                 const int key = ai * HALF + wr * 64 + m * 16 + fr;
;                 const float sc = __builtin_amdgcn_rsqf(ss_in[u.pm * BM + key] * (1.0f / DM) + EPS);
;                 f32x4 v[2][2]; float sq = 0.f;
; #pragma unroll
;                 for (int bj = 0; bj < 2; ++bj)
; #pragma unroll
;                     for (int n = 0; n < 2; ++n) { v[bj][n] = acc[ai][bj][m][n] * sc; const f32x4 t = v[bj][n]; sq += (t[0] * t[0] + t[1] * t[1]) + (t[2] * t[2] + t[3] * t[3]); }
;                 float rn = 1.f;
;                 if (isk) { sq += __shfl_xor(sq, 16); sq += __shfl_xor(sq, 32); rn = __builtin_amdgcn_rsqf(sq * (1.0f / HD) + EPS); }
; #pragma unroll
;                 for (int bj = 0; bj < 2; ++bj) {
;                     const f32x4 a = v[bj][0] * rn * gv[bj][0], b = v[bj][1] * rn * gv[bj][1];
;                     u32x4 w; w.x = pkh(a[0], a[1]); w.y = pkh(a[2], a[3]); w.z = pkh(b[0], b[1]); w.w = pkh(b[2], b[3]);
;                     *(u32x4*)(dst + (size_t)key * HD + 32 * bj + 8 * fq) = w;
;                 }
.LBB0_162:
	v_ashrrev_i32_e32 v37, 31, v36
	v_pk_mul_f32 v[32:33], v[32:33], v[38:39] op_sel_hi:[1,0]
	v_pk_mul_f32 v[30:31], v[30:31], v[38:39] op_sel_hi:[1,0]
	v_pk_mul_f32 v[28:29], v[28:29], v[38:39] op_sel_hi:[1,0]
	v_pk_mul_f32 v[26:27], v[26:27], v[38:39] op_sel_hi:[1,0]
	v_lshlrev_b64 v[36:37], 7, v[36:37]
	v_pk_mul_f32 v[32:33], v[88:89], v[32:33]
	v_pk_mul_f32 v[30:31], v[86:87], v[30:31]
	v_pk_mul_f32 v[40:41], v[84:85], v[28:29]
	v_pk_mul_f32 v[28:29], v[82:83], v[26:27]
	v_lshl_add_u64 v[36:37], v[130:131], 0, v[36:37]
	v_cvt_pk_f16_f32 v26, v30, v31
	v_cvt_pk_f16_f32 v27, v32, v33
	v_cvt_pk_f16_f32 v28, v28, v29
	v_cvt_pk_f16_f32 v29, v40, v41
	v_pk_mul_f32 v[24:25], v[24:25], v[38:39] op_sel_hi:[1,0]
	v_pk_mul_f32 v[22:23], v[22:23], v[38:39] op_sel_hi:[1,0]
	v_pk_mul_f32 v[20:21], v[20:21], v[38:39] op_sel_hi:[1,0]
	v_pk_mul_f32 v[18:19], v[18:19], v[38:39] op_sel_hi:[1,0]
	global_store_dwordx4 v[36:37], v[26:29], off
	v_pk_mul_f32 v[24:25], v[96:97], v[24:25]
	v_pk_mul_f32 v[22:23], v[94:95], v[22:23]
	v_pk_mul_f32 v[26:27], v[92:93], v[20:21]
	v_pk_mul_f32 v[20:21], v[90:91], v[18:19]
	v_cvt_pk_f16_f32 v18, v22, v23
	v_cvt_pk_f16_f32 v19, v24, v25
	v_cvt_pk_f16_f32 v20, v20, v21
	v_cvt_pk_f16_f32 v21, v26, v27
	global_store_dwordx4 v[36:37], v[18:21], off offset:64
	s_and_b64 vcc, exec, s[0:1]
	s_nop 0
	v_add_u32_e32 v18, 0xb0, v158
	v_add_u32_e32 v20, s23, v18
	v_ashrrev_i32_e32 v21, 31, v20
	v_lshl_add_u64 v[20:21], v[20:21], 2, s[4:5]
	global_load_dword v19, v[20:21], off
	s_waitcnt vmcnt(0)
	v_fmamk_f32 v19, v19, 0x3a800000, v174
	v_rsq_f32_e32 v20, v19
	s_nop 0
	v_pk_mul_f32 v[16:17], v[16:17], v[20:21] op_sel_hi:[1,0]
	v_pk_mul_f32 v[14:15], v[14:15], v[20:21] op_sel_hi:[1,0]
	v_pk_mul_f32 v[12:13], v[12:13], v[20:21] op_sel_hi:[1,0]
	v_pk_mul_f32 v[10:11], v[10:11], v[20:21] op_sel_hi:[1,0]
	v_pk_mul_f32 v[8:9], v[8:9], v[20:21] op_sel_hi:[1,0]
	v_pk_mul_f32 v[6:7], v[6:7], v[20:21] op_sel_hi:[1,0]
	v_pk_mul_f32 v[4:5], v[4:5], v[20:21] op_sel_hi:[1,0]
	v_pk_mul_f32 v[2:3], v[2:3], v[20:21] op_sel_hi:[1,0]
	s_cbranch_vccnz .LBB0_164
	v_pk_mul_f32 v[20:21], v[16:17], v[16:17]
	v_pk_mul_f32 v[22:23], v[14:15], v[14:15]
	s_nop 0
	v_pk_mov_b32 v[24:25], v[22:23], v[20:21] op_sel:[1,0]
	v_mov_b32_e32 v23, v21
	v_pk_add_f32 v[20:21], v[24:25], v[22:23]
	v_pk_mul_f32 v[22:23], v[12:13], v[12:13]
	v_pk_add_f32 v[20:21], v[20:21], v[20:21] op_sel_hi:[0,1]
	v_pk_mul_f32 v[24:25], v[10:11], v[10:11]
	v_mul_f32_e32 v20, v6, v6
	v_pk_mov_b32 v[26:27], v[24:25], v[22:23] op_sel:[1,0]
	v_mov_b32_e32 v25, v23
	v_pk_add_f32 v[22:23], v[26:27], v[24:25]
	v_pk_fma_f32 v[24:25], v[6:7], v[6:7], v[20:21] op_sel_hi:[1,1,0]
	v_mul_f32_e32 v20, v8, v8
	v_pk_add_f32 v[22:23], v[22:23], v[22:23] op_sel_hi:[0,1]
	v_pk_fma_f32 v[26:27], v[8:9], v[8:9], v[20:21] op_sel_hi:[1,1,0]
	v_mul_f32_e32 v24, v2, v2
	v_mul_f32_e32 v26, v3, v3
	v_mul_f32_e32 v20, v4, v4
	v_mul_f32_e32 v22, v5, v5
	v_pk_add_f32 v[24:25], v[24:25], v[26:27]
	v_pk_add_f32 v[20:21], v[20:21], v[22:23]
	s_nop 0
	v_pk_add_f32 v[20:21], v[24:25], v[20:21]
	s_nop 0
	v_add_f32_e32 v19, v20, v21
	v_and_b32_e32 v21, 64, v175
	v_xor_b32_e32 v20, 16, v175
	v_add_u32_e32 v21, 64, v21
	v_cmp_lt_i32_e32 vcc, v20, v21
	s_nop 1
	v_cndmask_b32_e32 v20, v175, v20, vcc
	v_lshlrev_b32_e32 v20, 2, v20
	v_mov_b32_e32 v20, v19
	s_nop 1
	v_permlane16_swap_b32_e32 v19, v20
	v_add_f32_e32 v19, v19, v20
	v_xor_b32_e32 v20, 32, v175
	v_cmp_lt_i32_e32 vcc, v20, v21
	s_nop 1
	v_cndmask_b32_e32 v20, v175, v20, vcc
	v_lshlrev_b32_e32 v20, 2, v20
	v_mov_b32_e32 v20, v19
	s_nop 1
	v_permlane32_swap_b32_e32 v19, v20
	v_add_f32_e32 v19, v19, v20
	v_fmamk_f32 v19, v19, 0x3c800000, v174
	v_rsq_f32_e32 v34, v19

; __device__ __forceinline__ unsigned pkh(float lo, float hi) { f32x2 v = {lo, hi}; h16x2 h = __builtin_convertvector(v, h16x2); return __builtin_bit_cast(unsigned, h); }
;     __device__ __forceinline__ void operator()(f32x4 (&acc)[2][2][4][2], const Unit& u, const Order& S, int wr, int wc, int fr_, int fq_, LAS unsigned char*, int) const {
;     ...
;                 for (int bj = 0; bj < 2; ++bj) {
;                     f32x4 v0 = acc[ai][bj][m][0] * sc, v1 = acc[ai][bj][m][1] * sc;
;                     if (act) { const f32x2 a0 = gelu_tanh2((f32x2){v0[0], v0[1]}), a1 = gelu_tanh2((f32x2){v0[2], v0[3]}), a2 = gelu_tanh2((f32x2){v1[0], v1[1]}), a3 = gelu_tanh2((f32x2){v1[2], v1[3]});
;                         v0 = (f32x4){a0.x, a0.y, a1.x, a1.y}; v1 = (f32x4){a2.x, a2.y, a3.x, a3.y}; }
;                     sq += (v0[0] * v0[0] + v0[1] * v0[1]) + (v0[2] * v0[2] + v0[3] * v0[3]) + (v1[0] * v1[0] + v1[1] * v1[1]) + (v1[2] * v1[2] + v1[3] * v1[3]);
;                     u32x4 w; w.x = pkh(v0[0], v0[1]); w.y = pkh(v0[2], v0[3]); w.z = pkh(v1[0], v1[1]); w.w = pkh(v1[2], v1[3]);
;                     *(u32x4*)(P + (size_t)row * NA + col0 + bj * HALF) = w;
;                 }
;                 if (stat && !dry) { sq += __shfl_xor(sq, 16); sq += __shfl_xor(sq, 32); if (fq == 0) atomicAdd(ssv + row, sq); }
.LBB0_186:
	s_add_i32 s2, s2, -6
	s_cmp_gt_u32 s2, -4
	s_cselect_b64 s[40:41], -1, 0
	s_cmp_lt_u32 s2, -3
	v_cmp_eq_u32_e64 s[2:3], 0, v158
	v_cvt_pk_f16_f32 v162, v118, v119
	v_cvt_pk_f16_f32 v163, v120, v121
	v_cvt_pk_f16_f32 v164, v114, v115
	v_cvt_pk_f16_f32 v165, v116, v117
	global_store_dwordx4 v[142:143], v[162:165], off offset:256
	s_cbranch_scc1 .LBB0_190
	v_mul_f32_e32 v127, v127, v127
	v_mul_f32_e32 v117, v117, v117
	v_mul_f32_e32 v115, v115, v115
	v_fmac_f32_e32 v127, v126, v126
	v_mul_f32_e32 v126, v129, v129
	v_fmac_f32_e32 v117, v116, v116
	v_fmac_f32_e32 v115, v114, v114
	v_mul_f32_e32 v114, v119, v119
	v_mul_f32_e32 v116, v121, v121
	v_fmac_f32_e32 v126, v128, v128
	v_fmac_f32_e32 v114, v118, v118
	v_fmac_f32_e32 v116, v120, v120
	v_add_f32_e32 v126, v127, v126
	v_mul_f32_e32 v127, v139, v139
	v_add_f32_e32 v114, v114, v116
	v_and_b32_e32 v116, 64, v157
	v_fmac_f32_e32 v127, v138, v138
	v_mul_f32_e32 v125, v125, v125
	v_add_f32_e32 v114, v115, v114
	v_xor_b32_e32 v115, 16, v157
	v_add_u32_e32 v116, 64, v116
	v_add_f32_e32 v126, v127, v126
	v_fmac_f32_e32 v125, v124, v124
	v_cmp_lt_i32_e32 vcc, v115, v116
	v_add_f32_e32 v124, v125, v126
	v_add_f32_e32 v114, v117, v114
	v_cndmask_b32_e32 v115, v157, v115, vcc
	v_add_f32_e32 v114, v124, v114
	v_lshlrev_b32_e32 v115, 2, v115
	v_mov_b32_e32 v115, v114
	s_nop 1
	v_permlane16_swap_b32_e32 v114, v115
	v_add_f32_e32 v114, v114, v115
	v_xor_b32_e32 v115, 32, v157
	v_cmp_lt_i32_e32 vcc, v115, v116
	s_nop 1
	v_cndmask_b32_e32 v115, v157, v115, vcc
	v_lshlrev_b32_e32 v115, 2, v115
	ds_bpermute_b32 v115, v115, v114
	s_and_saveexec_b64 s[6:7], s[2:3]
	s_cbranch_execz .LBB0_189
	v_lshl_add_u64 v[116:117], v[134:135], 2, s[12:13]
	s_waitcnt lgkmcnt(0)
	v_add_f32_e32 v114, v114, v115
	global_atomic_add_f32 v[116:117], v114, off

; __device__ __forceinline__ unsigned pkh(float lo, float hi) { f32x2 v = {lo, hi}; h16x2 h = __builtin_convertvector(v, h16x2); return __builtin_bit_cast(unsigned, h); }
;     __device__ __forceinline__ void operator()(f32x4 (&acc)[2][2][4][2], const Unit& u, const Order& S, int wr, int wc, int fr_, int fq_, LAS unsigned char*, int) const {
;     ...
;                 for (int bj = 0; bj < 2; ++bj) {
;                     f32x4 v0 = acc[ai][bj][m][0] * sc, v1 = acc[ai][bj][m][1] * sc;
;                     if (act) { const f32x2 a0 = gelu_tanh2((f32x2){v0[0], v0[1]}), a1 = gelu_tanh2((f32x2){v0[2], v0[3]}), a2 = gelu_tanh2((f32x2){v1[0], v1[1]}), a3 = gelu_tanh2((f32x2){v1[2], v1[3]});
;                         v0 = (f32x4){a0.x, a0.y, a1.x, a1.y}; v1 = (f32x4){a2.x, a2.y, a3.x, a3.y}; }
;                     sq += (v0[0] * v0[0] + v0[1] * v0[1]) + (v0[2] * v0[2] + v0[3] * v0[3]) + (v1[0] * v1[0] + v1[1] * v1[1]) + (v1[2] * v1[2] + v1[3] * v1[3]);
;                     u32x4 w; w.x = pkh(v0[0], v0[1]); w.y = pkh(v0[2], v0[3]); w.z = pkh(v1[0], v1[1]); w.w = pkh(v1[2], v1[3]);
;                     *(u32x4*)(P + (size_t)row * NA + col0 + bj * HALF) = w;
;                 }
;                 if (stat && !dry) { sq += __shfl_xor(sq, 16); sq += __shfl_xor(sq, 32); if (fq == 0) atomicAdd(ssv + row, sq); }
.LBB0_194:
	s_waitcnt lgkmcnt(0)
	v_cndmask_b32_e64 v115, 0, 1, s[40:41]
	v_cvt_pk_f16_f32 v124, v102, v103
	v_cvt_pk_f16_f32 v125, v104, v105
	v_cvt_pk_f16_f32 v126, v98, v99
	v_cvt_pk_f16_f32 v127, v100, v101
	v_cmp_ne_u32_e64 s[6:7], 1, v115
	s_andn2_b64 vcc, exec, s[40:41]
	global_store_dwordx4 v[118:119], v[124:127], off offset:256
	s_cbranch_vccnz .LBB0_198
	v_mul_f32_e32 v111, v111, v111
	v_mul_f32_e32 v101, v101, v101
	v_mul_f32_e32 v99, v99, v99
	v_fmac_f32_e32 v111, v110, v110
	v_mul_f32_e32 v110, v113, v113
	v_fmac_f32_e32 v101, v100, v100
	v_fmac_f32_e32 v99, v98, v98
	v_mul_f32_e32 v98, v103, v103
	v_mul_f32_e32 v100, v105, v105
	v_fmac_f32_e32 v110, v112, v112
	v_mul_f32_e32 v107, v107, v107
	v_fmac_f32_e32 v98, v102, v102
	v_fmac_f32_e32 v100, v104, v104
	v_add_f32_e32 v110, v111, v110
	v_fmac_f32_e32 v107, v106, v106
	v_add_f32_e32 v98, v98, v100
	v_and_b32_e32 v100, 64, v157
	v_add_f32_e32 v106, v107, v110
	v_mul_f32_e32 v107, v109, v109
	v_add_f32_e32 v98, v99, v98
	v_xor_b32_e32 v99, 16, v157
	v_add_u32_e32 v100, 64, v100
	v_fmac_f32_e32 v107, v108, v108
	v_cmp_lt_i32_e32 vcc, v99, v100
	v_add_f32_e32 v106, v107, v106
	v_add_f32_e32 v98, v101, v98
	v_cndmask_b32_e32 v99, v157, v99, vcc
	v_add_f32_e32 v98, v106, v98
	v_lshlrev_b32_e32 v99, 2, v99
	v_mov_b32_e32 v99, v98
	s_nop 1
	v_permlane16_swap_b32_e32 v98, v99
	v_add_f32_e32 v98, v98, v99
	v_xor_b32_e32 v99, 32, v157
	v_cmp_lt_i32_e32 vcc, v99, v100
	s_nop 1
	v_cndmask_b32_e32 v99, v157, v99, vcc
	v_lshlrev_b32_e32 v99, 2, v99
	ds_bpermute_b32 v99, v99, v98
	s_and_saveexec_b64 s[40:41], s[2:3]
	s_cbranch_execz .LBB0_197
	v_ashrrev_i32_e32 v115, 31, v114
	v_lshl_add_u64 v[100:101], v[114:115], 2, s[12:13]
	s_waitcnt lgkmcnt(0)
	v_add_f32_e32 v98, v98, v99
	global_atomic_add_f32 v[100:101], v98, off

; __device__ __forceinline__ unsigned pkh(float lo, float hi) { f32x2 v = {lo, hi}; h16x2 h = __builtin_convertvector(v, h16x2); return __builtin_bit_cast(unsigned, h); }
;     __device__ __forceinline__ void operator()(f32x4 (&acc)[2][2][4][2], const Unit& u, const Order& S, int wr, int wc, int fr_, int fq_, LAS unsigned char*, int) const {
;     ...
;                 for (int bj = 0; bj < 2; ++bj) {
;                     f32x4 v0 = acc[ai][bj][m][0] * sc, v1 = acc[ai][bj][m][1] * sc;
;                     if (act) { const f32x2 a0 = gelu_tanh2((f32x2){v0[0], v0[1]}), a1 = gelu_tanh2((f32x2){v0[2], v0[3]}), a2 = gelu_tanh2((f32x2){v1[0], v1[1]}), a3 = gelu_tanh2((f32x2){v1[2], v1[3]});
;                         v0 = (f32x4){a0.x, a0.y, a1.x, a1.y}; v1 = (f32x4){a2.x, a2.y, a3.x, a3.y}; }
;                     sq += (v0[0] * v0[0] + v0[1] * v0[1]) + (v0[2] * v0[2] + v0[3] * v0[3]) + (v1[0] * v1[0] + v1[1] * v1[1]) + (v1[2] * v1[2] + v1[3] * v1[3]);
;                     u32x4 w; w.x = pkh(v0[0], v0[1]); w.y = pkh(v0[2], v0[3]); w.z = pkh(v1[0], v1[1]); w.w = pkh(v1[2], v1[3]);
;                     *(u32x4*)(P + (size_t)row * NA + col0 + bj * HALF) = w;
;                 }
;                 if (stat && !dry) { sq += __shfl_xor(sq, 16); sq += __shfl_xor(sq, 32); if (fq == 0) atomicAdd(ssv + row, sq); }
.LBB0_202:
	v_cvt_pk_f16_f32 v104, v86, v87
	v_cvt_pk_f16_f32 v105, v88, v89
	v_cvt_pk_f16_f32 v106, v82, v83
	v_cvt_pk_f16_f32 v107, v84, v85
	s_and_b64 vcc, exec, s[6:7]
	global_store_dwordx4 v[102:103], v[104:107], off offset:256
	s_cbranch_vccnz .LBB0_206
	v_mul_f32_e32 v95, v95, v95
	v_mul_f32_e32 v85, v85, v85
	v_mul_f32_e32 v83, v83, v83
	v_fmac_f32_e32 v95, v94, v94
	v_mul_f32_e32 v94, v97, v97
	v_fmac_f32_e32 v85, v84, v84
	v_fmac_f32_e32 v83, v82, v82
	v_mul_f32_e32 v82, v87, v87
	v_mul_f32_e32 v84, v89, v89
	v_fmac_f32_e32 v94, v96, v96
	v_mul_f32_e32 v91, v91, v91
	v_fmac_f32_e32 v82, v86, v86
	v_fmac_f32_e32 v84, v88, v88
	v_add_f32_e32 v94, v95, v94
	v_fmac_f32_e32 v91, v90, v90
	v_add_f32_e32 v82, v82, v84
	v_and_b32_e32 v84, 64, v157
	v_add_f32_e32 v90, v91, v94
	v_mul_f32_e32 v91, v93, v93
	v_add_f32_e32 v82, v83, v82
	v_xor_b32_e32 v83, 16, v157
	v_add_u32_e32 v84, 64, v84
	v_fmac_f32_e32 v91, v92, v92
	v_cmp_lt_i32_e32 vcc, v83, v84
	v_add_f32_e32 v90, v91, v90
	v_add_f32_e32 v82, v85, v82
	v_cndmask_b32_e32 v83, v157, v83, vcc
	v_add_f32_e32 v82, v90, v82
	v_lshlrev_b32_e32 v83, 2, v83
	v_mov_b32_e32 v83, v82
	s_nop 1
	v_permlane16_swap_b32_e32 v82, v83
	v_add_f32_e32 v82, v82, v83
	v_xor_b32_e32 v83, 32, v157
	v_cmp_lt_i32_e32 vcc, v83, v84
	s_nop 1
	v_cndmask_b32_e32 v83, v157, v83, vcc
	v_lshlrev_b32_e32 v83, 2, v83
	ds_bpermute_b32 v83, v83, v82
	s_and_saveexec_b64 s[40:41], s[2:3]
	s_cbranch_execz .LBB0_205
	v_ashrrev_i32_e32 v99, 31, v98
	v_lshl_add_u64 v[84:85], v[98:99], 2, s[12:13]
	s_waitcnt lgkmcnt(0)
	v_add_f32_e32 v82, v82, v83
	global_atomic_add_f32 v[84:85], v82, off

; __device__ __forceinline__ unsigned pkh(float lo, float hi) { f32x2 v = {lo, hi}; h16x2 h = __builtin_convertvector(v, h16x2); return __builtin_bit_cast(unsigned, h); }
;     __device__ __forceinline__ void operator()(f32x4 (&acc)[2][2][4][2], const Unit& u, const Order& S, int wr, int wc, int fr_, int fq_, LAS unsigned char*, int) const {
;     ...
;                 for (int bj = 0; bj < 2; ++bj) {
;                     f32x4 v0 = acc[ai][bj][m][0] * sc, v1 = acc[ai][bj][m][1] * sc;
;                     if (act) { const f32x2 a0 = gelu_tanh2((f32x2){v0[0], v0[1]}), a1 = gelu_tanh2((f32x2){v0[2], v0[3]}), a2 = gelu_tanh2((f32x2){v1[0], v1[1]}), a3 = gelu_tanh2((f32x2){v1[2], v1[3]});
;                         v0 = (f32x4){a0.x, a0.y, a1.x, a1.y}; v1 = (f32x4){a2.x, a2.y, a3.x, a3.y}; }
;                     sq += (v0[0] * v0[0] + v0[1] * v0[1]) + (v0[2] * v0[2] + v0[3] * v0[3]) + (v1[0] * v1[0] + v1[1] * v1[1]) + (v1[2] * v1[2] + v1[3] * v1[3]);
;                     u32x4 w; w.x = pkh(v0[0], v0[1]); w.y = pkh(v0[2], v0[3]); w.z = pkh(v1[0], v1[1]); w.w = pkh(v1[2], v1[3]);
;                     *(u32x4*)(P + (size_t)row * NA + col0 + bj * HALF) = w;
;                 }
;                 if (stat && !dry) { sq += __shfl_xor(sq, 16); sq += __shfl_xor(sq, 32); if (fq == 0) atomicAdd(ssv + row, sq); }
.LBB0_210:
	v_cvt_pk_f16_f32 v88, v70, v71
	v_cvt_pk_f16_f32 v89, v72, v73
	v_cvt_pk_f16_f32 v90, v66, v67
	v_cvt_pk_f16_f32 v91, v68, v69
	s_and_b64 vcc, exec, s[6:7]
	global_store_dwordx4 v[86:87], v[88:91], off offset:256
	s_cbranch_vccnz .LBB0_214
	v_mul_f32_e32 v79, v79, v79
	v_mul_f32_e32 v69, v69, v69
	v_mul_f32_e32 v67, v67, v67
	v_fmac_f32_e32 v79, v78, v78
	v_mul_f32_e32 v78, v81, v81
	v_fmac_f32_e32 v69, v68, v68
	v_fmac_f32_e32 v67, v66, v66
	v_mul_f32_e32 v66, v71, v71
	v_mul_f32_e32 v68, v73, v73
	v_fmac_f32_e32 v78, v80, v80
	v_mul_f32_e32 v75, v75, v75
	v_fmac_f32_e32 v66, v70, v70
	v_fmac_f32_e32 v68, v72, v72
	v_add_f32_e32 v78, v79, v78
	v_fmac_f32_e32 v75, v74, v74
	v_add_f32_e32 v66, v66, v68
	v_and_b32_e32 v68, 64, v157
	v_add_f32_e32 v74, v75, v78
	v_mul_f32_e32 v75, v77, v77
	v_add_f32_e32 v66, v67, v66
	v_xor_b32_e32 v67, 16, v157
	v_add_u32_e32 v68, 64, v68
	v_fmac_f32_e32 v75, v76, v76
	v_cmp_lt_i32_e32 vcc, v67, v68
	v_add_f32_e32 v74, v75, v74
	v_add_f32_e32 v66, v69, v66
	v_cndmask_b32_e32 v67, v157, v67, vcc
	v_add_f32_e32 v66, v74, v66
	v_lshlrev_b32_e32 v67, 2, v67
	v_mov_b32_e32 v67, v66
	s_nop 1
	v_permlane16_swap_b32_e32 v66, v67
	v_add_f32_e32 v66, v66, v67
	v_xor_b32_e32 v67, 32, v157
	v_cmp_lt_i32_e32 vcc, v67, v68
	s_nop 1
	v_cndmask_b32_e32 v67, v157, v67, vcc
	v_lshlrev_b32_e32 v67, 2, v67
	ds_bpermute_b32 v67, v67, v66
	s_and_saveexec_b64 s[40:41], s[2:3]
	s_cbranch_execz .LBB0_213
	v_ashrrev_i32_e32 v83, 31, v82
	v_lshl_add_u64 v[68:69], v[82:83], 2, s[12:13]
	s_waitcnt lgkmcnt(0)
	v_add_f32_e32 v66, v66, v67
	global_atomic_add_f32 v[68:69], v66, off

; __device__ __forceinline__ unsigned pkh(float lo, float hi) { f32x2 v = {lo, hi}; h16x2 h = __builtin_convertvector(v, h16x2); return __builtin_bit_cast(unsigned, h); }
;     __device__ __forceinline__ void operator()(f32x4 (&acc)[2][2][4][2], const Unit& u, const Order& S, int wr, int wc, int fr_, int fq_, LAS unsigned char*, int) const {
;     ...
;                 for (int bj = 0; bj < 2; ++bj) {
;                     f32x4 v0 = acc[ai][bj][m][0] * sc, v1 = acc[ai][bj][m][1] * sc;
;                     if (act) { const f32x2 a0 = gelu_tanh2((f32x2){v0[0], v0[1]}), a1 = gelu_tanh2((f32x2){v0[2], v0[3]}), a2 = gelu_tanh2((f32x2){v1[0], v1[1]}), a3 = gelu_tanh2((f32x2){v1[2], v1[3]});
;                         v0 = (f32x4){a0.x, a0.y, a1.x, a1.y}; v1 = (f32x4){a2.x, a2.y, a3.x, a3.y}; }
;                     sq += (v0[0] * v0[0] + v0[1] * v0[1]) + (v0[2] * v0[2] + v0[3] * v0[3]) + (v1[0] * v1[0] + v1[1] * v1[1]) + (v1[2] * v1[2] + v1[3] * v1[3]);
;                     u32x4 w; w.x = pkh(v0[0], v0[1]); w.y = pkh(v0[2], v0[3]); w.z = pkh(v1[0], v1[1]); w.w = pkh(v1[2], v1[3]);
;                     *(u32x4*)(P + (size_t)row * NA + col0 + bj * HALF) = w;
;                 }
;                 if (stat && !dry) { sq += __shfl_xor(sq, 16); sq += __shfl_xor(sq, 32); if (fq == 0) atomicAdd(ssv + row, sq); }
.LBB0_218:
	v_cvt_pk_f16_f32 v72, v54, v55
	v_cvt_pk_f16_f32 v73, v56, v57
	v_cvt_pk_f16_f32 v74, v50, v51
	v_cvt_pk_f16_f32 v75, v52, v53
	s_and_b64 vcc, exec, s[6:7]
	global_store_dwordx4 v[70:71], v[72:75], off offset:256
	s_cbranch_vccnz .LBB0_222
	v_mul_f32_e32 v63, v63, v63
	v_mul_f32_e32 v53, v53, v53
	v_mul_f32_e32 v51, v51, v51
	v_fmac_f32_e32 v63, v62, v62
	v_mul_f32_e32 v62, v65, v65
	v_fmac_f32_e32 v53, v52, v52
	v_fmac_f32_e32 v51, v50, v50
	v_mul_f32_e32 v50, v55, v55
	v_mul_f32_e32 v52, v57, v57
	v_fmac_f32_e32 v62, v64, v64
	v_mul_f32_e32 v59, v59, v59
	v_fmac_f32_e32 v50, v54, v54
	v_fmac_f32_e32 v52, v56, v56
	v_add_f32_e32 v62, v63, v62
	v_fmac_f32_e32 v59, v58, v58
	v_add_f32_e32 v50, v50, v52
	v_and_b32_e32 v52, 64, v157
	v_add_f32_e32 v58, v59, v62
	v_mul_f32_e32 v59, v61, v61
	v_add_f32_e32 v50, v51, v50
	v_xor_b32_e32 v51, 16, v157
	v_add_u32_e32 v52, 64, v52
	v_fmac_f32_e32 v59, v60, v60
	v_cmp_lt_i32_e32 vcc, v51, v52
	v_add_f32_e32 v58, v59, v58
	v_add_f32_e32 v50, v53, v50
	v_cndmask_b32_e32 v51, v157, v51, vcc
	v_add_f32_e32 v50, v58, v50
	v_lshlrev_b32_e32 v51, 2, v51
	v_mov_b32_e32 v51, v50
	s_nop 1
	v_permlane16_swap_b32_e32 v50, v51
	v_add_f32_e32 v50, v50, v51
	v_xor_b32_e32 v51, 32, v157
	v_cmp_lt_i32_e32 vcc, v51, v52
	s_nop 1
	v_cndmask_b32_e32 v51, v157, v51, vcc
	v_lshlrev_b32_e32 v51, 2, v51
	ds_bpermute_b32 v51, v51, v50
	s_and_saveexec_b64 s[40:41], s[2:3]
	s_cbranch_execz .LBB0_221
	v_ashrrev_i32_e32 v67, 31, v66
	v_lshl_add_u64 v[52:53], v[66:67], 2, s[12:13]
	s_waitcnt lgkmcnt(0)
	v_add_f32_e32 v50, v50, v51
	global_atomic_add_f32 v[52:53], v50, off

; __device__ __forceinline__ unsigned pkh(float lo, float hi) { f32x2 v = {lo, hi}; h16x2 h = __builtin_convertvector(v, h16x2); return __builtin_bit_cast(unsigned, h); }
;     __device__ __forceinline__ void operator()(f32x4 (&acc)[2][2][4][2], const Unit& u, const Order& S, int wr, int wc, int fr_, int fq_, LAS unsigned char*, int) const {
;     ...
;                 for (int bj = 0; bj < 2; ++bj) {
;                     f32x4 v0 = acc[ai][bj][m][0] * sc, v1 = acc[ai][bj][m][1] * sc;
;                     if (act) { const f32x2 a0 = gelu_tanh2((f32x2){v0[0], v0[1]}), a1 = gelu_tanh2((f32x2){v0[2], v0[3]}), a2 = gelu_tanh2((f32x2){v1[0], v1[1]}), a3 = gelu_tanh2((f32x2){v1[2], v1[3]});
;                         v0 = (f32x4){a0.x, a0.y, a1.x, a1.y}; v1 = (f32x4){a2.x, a2.y, a3.x, a3.y}; }
;                     sq += (v0[0] * v0[0] + v0[1] * v0[1]) + (v0[2] * v0[2] + v0[3] * v0[3]) + (v1[0] * v1[0] + v1[1] * v1[1]) + (v1[2] * v1[2] + v1[3] * v1[3]);
;                     u32x4 w; w.x = pkh(v0[0], v0[1]); w.y = pkh(v0[2], v0[3]); w.z = pkh(v1[0], v1[1]); w.w = pkh(v1[2], v1[3]);
;                     *(u32x4*)(P + (size_t)row * NA + col0 + bj * HALF) = w;
;                 }
;                 if (stat && !dry) { sq += __shfl_xor(sq, 16); sq += __shfl_xor(sq, 32); if (fq == 0) atomicAdd(ssv + row, sq); }
.LBB0_226:
	v_cvt_pk_f16_f32 v56, v38, v39
	v_cvt_pk_f16_f32 v57, v40, v41
	v_cvt_pk_f16_f32 v58, v34, v35
	v_cvt_pk_f16_f32 v59, v36, v37
	s_and_b64 vcc, exec, s[6:7]
	global_store_dwordx4 v[54:55], v[56:59], off offset:256
	s_cbranch_vccnz .LBB0_230
	v_mul_f32_e32 v47, v47, v47
	v_mul_f32_e32 v37, v37, v37
	v_mul_f32_e32 v35, v35, v35
	v_fmac_f32_e32 v47, v46, v46
	v_mul_f32_e32 v46, v49, v49
	v_fmac_f32_e32 v37, v36, v36
	v_fmac_f32_e32 v35, v34, v34
	v_mul_f32_e32 v34, v39, v39
	v_mul_f32_e32 v36, v41, v41
	v_fmac_f32_e32 v46, v48, v48
	v_mul_f32_e32 v43, v43, v43
	v_fmac_f32_e32 v34, v38, v38
	v_fmac_f32_e32 v36, v40, v40
	v_add_f32_e32 v46, v47, v46
	v_fmac_f32_e32 v43, v42, v42
	v_add_f32_e32 v34, v34, v36
	v_and_b32_e32 v36, 64, v157
	v_add_f32_e32 v42, v43, v46
	v_mul_f32_e32 v43, v45, v45
	v_add_f32_e32 v34, v35, v34
	v_xor_b32_e32 v35, 16, v157
	v_add_u32_e32 v36, 64, v36
	v_fmac_f32_e32 v43, v44, v44
	v_cmp_lt_i32_e32 vcc, v35, v36
	v_add_f32_e32 v42, v43, v42
	v_add_f32_e32 v34, v37, v34
	v_cndmask_b32_e32 v35, v157, v35, vcc
	v_add_f32_e32 v34, v42, v34
	v_lshlrev_b32_e32 v35, 2, v35
	v_mov_b32_e32 v35, v34
	s_nop 1
	v_permlane16_swap_b32_e32 v34, v35
	v_add_f32_e32 v34, v34, v35
	v_xor_b32_e32 v35, 32, v157
	v_cmp_lt_i32_e32 vcc, v35, v36
	s_nop 1
	v_cndmask_b32_e32 v35, v157, v35, vcc
	v_lshlrev_b32_e32 v35, 2, v35
	ds_bpermute_b32 v35, v35, v34
	s_and_saveexec_b64 s[40:41], s[2:3]
	s_cbranch_execz .LBB0_229
	v_ashrrev_i32_e32 v51, 31, v50
	v_lshl_add_u64 v[36:37], v[50:51], 2, s[12:13]
	s_waitcnt lgkmcnt(0)
	v_add_f32_e32 v34, v34, v35
	global_atomic_add_f32 v[36:37], v34, off

; __device__ __forceinline__ unsigned pkh(float lo, float hi) { f32x2 v = {lo, hi}; h16x2 h = __builtin_convertvector(v, h16x2); return __builtin_bit_cast(unsigned, h); }
;     __device__ __forceinline__ void operator()(f32x4 (&acc)[2][2][4][2], const Unit& u, const Order& S, int wr, int wc, int fr_, int fq_, LAS unsigned char*, int) const {
;     ...
;                 for (int bj = 0; bj < 2; ++bj) {
;                     f32x4 v0 = acc[ai][bj][m][0] * sc, v1 = acc[ai][bj][m][1] * sc;
;                     if (act) { const f32x2 a0 = gelu_tanh2((f32x2){v0[0], v0[1]}), a1 = gelu_tanh2((f32x2){v0[2], v0[3]}), a2 = gelu_tanh2((f32x2){v1[0], v1[1]}), a3 = gelu_tanh2((f32x2){v1[2], v1[3]});
;                         v0 = (f32x4){a0.x, a0.y, a1.x, a1.y}; v1 = (f32x4){a2.x, a2.y, a3.x, a3.y}; }
;                     sq += (v0[0] * v0[0] + v0[1] * v0[1]) + (v0[2] * v0[2] + v0[3] * v0[3]) + (v1[0] * v1[0] + v1[1] * v1[1]) + (v1[2] * v1[2] + v1[3] * v1[3]);
;                     u32x4 w; w.x = pkh(v0[0], v0[1]); w.y = pkh(v0[2], v0[3]); w.z = pkh(v1[0], v1[1]); w.w = pkh(v1[2], v1[3]);
;                     *(u32x4*)(P + (size_t)row * NA + col0 + bj * HALF) = w;
;                 }
;                 if (stat && !dry) { sq += __shfl_xor(sq, 16); sq += __shfl_xor(sq, 32); if (fq == 0) atomicAdd(ssv + row, sq); }
.LBB0_234:
	v_cvt_pk_f16_f32 v40, v22, v23
	v_cvt_pk_f16_f32 v41, v24, v25
	v_cvt_pk_f16_f32 v42, v18, v19
	v_cvt_pk_f16_f32 v43, v20, v21
	s_and_b64 vcc, exec, s[6:7]
	global_store_dwordx4 v[38:39], v[40:43], off offset:256
	s_cbranch_vccnz .LBB0_238
	v_mul_f32_e32 v31, v31, v31
	v_mul_f32_e32 v21, v21, v21
	v_mul_f32_e32 v19, v19, v19
	v_fmac_f32_e32 v31, v30, v30
	v_mul_f32_e32 v30, v33, v33
	v_fmac_f32_e32 v21, v20, v20
	v_fmac_f32_e32 v19, v18, v18
	v_mul_f32_e32 v18, v23, v23
	v_mul_f32_e32 v20, v25, v25
	v_fmac_f32_e32 v30, v32, v32
	v_mul_f32_e32 v27, v27, v27
	v_fmac_f32_e32 v18, v22, v22
	v_fmac_f32_e32 v20, v24, v24
	v_add_f32_e32 v30, v31, v30
	v_fmac_f32_e32 v27, v26, v26
	v_add_f32_e32 v18, v18, v20
	v_and_b32_e32 v20, 64, v157
	v_add_f32_e32 v26, v27, v30
	v_mul_f32_e32 v27, v29, v29
	v_add_f32_e32 v18, v19, v18
	v_xor_b32_e32 v19, 16, v157
	v_add_u32_e32 v20, 64, v20
	v_fmac_f32_e32 v27, v28, v28
	v_cmp_lt_i32_e32 vcc, v19, v20
	v_add_f32_e32 v26, v27, v26
	v_add_f32_e32 v18, v21, v18
	v_cndmask_b32_e32 v19, v157, v19, vcc
	v_add_f32_e32 v18, v26, v18
	v_lshlrev_b32_e32 v19, 2, v19
	v_mov_b32_e32 v19, v18
	s_nop 1
	v_permlane16_swap_b32_e32 v18, v19
	v_add_f32_e32 v18, v18, v19
	v_xor_b32_e32 v19, 32, v157
	v_cmp_lt_i32_e32 vcc, v19, v20
	s_nop 1
	v_cndmask_b32_e32 v19, v157, v19, vcc
	v_lshlrev_b32_e32 v19, 2, v19
	ds_bpermute_b32 v19, v19, v18
	s_and_saveexec_b64 s[40:41], s[2:3]
	s_cbranch_execz .LBB0_237
	v_ashrrev_i32_e32 v35, 31, v34
	v_lshl_add_u64 v[20:21], v[34:35], 2, s[12:13]
	s_waitcnt lgkmcnt(0)
	v_add_f32_e32 v18, v18, v19
	global_atomic_add_f32 v[20:21], v18, off

; __device__ __forceinline__ unsigned pkh(float lo, float hi) { f32x2 v = {lo, hi}; h16x2 h = __builtin_convertvector(v, h16x2); return __builtin_bit_cast(unsigned, h); }
;     __device__ __forceinline__ void operator()(f32x4 (&acc)[2][2][4][2], const Unit& u, const Order& S, int wr, int wc, int fr_, int fq_, LAS unsigned char*, int) const {
;     ...
;                 for (int bj = 0; bj < 2; ++bj) {
;                     f32x4 v0 = acc[ai][bj][m][0] * sc, v1 = acc[ai][bj][m][1] * sc;
;                     if (act) { const f32x2 a0 = gelu_tanh2((f32x2){v0[0], v0[1]}), a1 = gelu_tanh2((f32x2){v0[2], v0[3]}), a2 = gelu_tanh2((f32x2){v1[0], v1[1]}), a3 = gelu_tanh2((f32x2){v1[2], v1[3]});
;                         v0 = (f32x4){a0.x, a0.y, a1.x, a1.y}; v1 = (f32x4){a2.x, a2.y, a3.x, a3.y}; }
;                     sq += (v0[0] * v0[0] + v0[1] * v0[1]) + (v0[2] * v0[2] + v0[3] * v0[3]) + (v1[0] * v1[0] + v1[1] * v1[1]) + (v1[2] * v1[2] + v1[3] * v1[3]);
;                     u32x4 w; w.x = pkh(v0[0], v0[1]); w.y = pkh(v0[2], v0[3]); w.z = pkh(v1[0], v1[1]); w.w = pkh(v1[2], v1[3]);
;                     *(u32x4*)(P + (size_t)row * NA + col0 + bj * HALF) = w;
;                 }
;                 if (stat && !dry) { sq += __shfl_xor(sq, 16); sq += __shfl_xor(sq, 32); if (fq == 0) atomicAdd(ssv + row, sq); }
.LBB0_242:
	v_cvt_pk_f16_f32 v24, v6, v7
	v_cvt_pk_f16_f32 v25, v8, v9
	v_cvt_pk_f16_f32 v26, v2, v3
	v_cvt_pk_f16_f32 v27, v4, v5
	s_and_b64 vcc, exec, s[6:7]
	global_store_dwordx4 v[22:23], v[24:27], off offset:256
	s_cbranch_vccnz .LBB0_246
	v_mul_f32_e32 v15, v15, v15
	v_mul_f32_e32 v5, v5, v5
	v_mul_f32_e32 v3, v3, v3
	v_fmac_f32_e32 v15, v14, v14
	v_mul_f32_e32 v14, v17, v17
	v_fmac_f32_e32 v5, v4, v4
	v_fmac_f32_e32 v3, v2, v2
	v_mul_f32_e32 v2, v7, v7
	v_mul_f32_e32 v4, v9, v9
	v_fmac_f32_e32 v14, v16, v16
	v_mul_f32_e32 v11, v11, v11
	v_fmac_f32_e32 v2, v6, v6
	v_fmac_f32_e32 v4, v8, v8
	v_add_f32_e32 v14, v15, v14
	v_fmac_f32_e32 v11, v10, v10
	v_add_f32_e32 v2, v2, v4
	v_and_b32_e32 v4, 64, v157
	v_add_f32_e32 v10, v11, v14
	v_mul_f32_e32 v11, v13, v13
	v_add_f32_e32 v2, v3, v2
	v_xor_b32_e32 v3, 16, v157
	v_add_u32_e32 v4, 64, v4
	v_fmac_f32_e32 v11, v12, v12
	v_cmp_lt_i32_e32 vcc, v3, v4
	v_add_f32_e32 v10, v11, v10
	v_add_f32_e32 v2, v5, v2
	v_cndmask_b32_e32 v3, v157, v3, vcc
	v_add_f32_e32 v2, v10, v2
	v_lshlrev_b32_e32 v3, 2, v3
	v_mov_b32_e32 v3, v2
	s_nop 1
	v_permlane16_swap_b32_e32 v2, v3
	v_add_f32_e32 v2, v2, v3
	v_xor_b32_e32 v3, 32, v157
	v_cmp_lt_i32_e32 vcc, v3, v4
	s_nop 1
	v_cndmask_b32_e32 v3, v157, v3, vcc
	v_lshlrev_b32_e32 v3, 2, v3
	ds_bpermute_b32 v3, v3, v2
	s_and_saveexec_b64 s[4:5], s[2:3]
	s_cbranch_execz .LBB0_245
	v_ashrrev_i32_e32 v19, 31, v18
	v_lshl_add_u64 v[4:5], v[18:19], 2, s[12:13]
	s_waitcnt lgkmcnt(0)
	v_add_f32_e32 v2, v2, v3
	global_atomic_add_f32 v[4:5], v2, off

; __device__ __forceinline__ unsigned pkh(float lo, float hi) { f32x2 v = {lo, hi}; h16x2 h = __builtin_convertvector(v, h16x2); return __builtin_bit_cast(unsigned, h); }
;     __device__ __forceinline__ void operator()(f32x4 (&acc)[2][2][4][2], const Unit& u, const Order& S, int wr, int wc, int fr_, int fq_, LAS unsigned char*, int) const {
;     ...
;         for (int ai = 0; ai < 2; ++ai)
; #pragma unroll
;             for (int m = 0; m < 4; ++m) {
;                 const int row = row0 + ai * HALF + m * 16;
;                 const float sc = __builtin_amdgcn_rsqf(ss_in[row] * (1.0f / DM) + EPS) * pre;
;                 f32x4 v[2][2]; float sq = 0.f;
; #pragma unroll
;                 for (int bj = 0; bj < 2; ++bj)
; #pragma unroll
;                     for (int n = 0; n < 2; ++n) { v[bj][n] = acc[ai][bj][m][n] * sc; const f32x4 t = v[bj][n]; sq += (t[0] * t[0] + t[1] * t[1]) + (t[2] * t[2] + t[3] * t[3]); }
;                 float rn = 1.f;
;                 if (nrm) { sq += __shfl_xor(sq, 16); sq += __shfl_xor(sq, 32); rn = __builtin_amdgcn_rsqf(sq * (1.0f / HD) + EPS); }
; #pragma unroll
;                 for (int bj = 0; bj < 2; ++bj) {
;                     const f32x4 a = v[bj][0] * rn * gv[bj][0], b = v[bj][1] * rn * gv[bj][1];
;                     ks[bj][0] += a; ks[bj][1] += b;
;                     u32x4 w; w.x = pkh(a[0], a[1]); w.y = pkh(a[2], a[3]); w.z = pkh(b[0], b[1]); w.w = pkh(b[2], b[3]);
;                     *(u32x4*)(P + (size_t)row * NB + colh + 32 * bj + 8 * fq) = w;
;                 }
.LBB0_761:
	s_lshl_b32 s17, s53, 8
	s_add_i32 s17, s17, s43
	v_add_u32_e32 v178, s17, v182
	v_ashrrev_i32_e32 v179, 31, v178
	v_lshl_add_u64 v[180:181], v[178:179], 2, s[4:5]
	global_load_dword v18, v[180:181], off
	v_mov_b32_e32 v26, 1.0
	s_and_b64 vcc, exec, s[2:3]
	s_waitcnt vmcnt(0)
	v_fmamk_f32 v18, v18, 0x3a800000, v192
	v_rsq_f32_e32 v18, v18
	s_nop 0
	v_mul_f32_e32 v20, 0x39800000, v18
	v_pk_mul_f32 v[160:161], v[160:161], v[20:21] op_sel_hi:[1,0]
	v_pk_mul_f32 v[158:159], v[158:159], v[20:21] op_sel_hi:[1,0]
	v_pk_mul_f32 v[30:31], v[156:157], v[20:21] op_sel_hi:[1,0]
	v_pk_mul_f32 v[32:33], v[154:155], v[20:21] op_sel_hi:[1,0]
	v_pk_mul_f32 v[22:23], v[152:153], v[20:21] op_sel_hi:[1,0]
	v_pk_mul_f32 v[28:29], v[150:151], v[20:21] op_sel_hi:[1,0]
	v_pk_mul_f32 v[18:19], v[148:149], v[20:21] op_sel_hi:[1,0]
	v_pk_mul_f32 v[20:21], v[146:147], v[20:21] op_sel_hi:[1,0]
	v_mov_b32_e32 v152, 1.0
	s_cbranch_vccnz .LBB0_763
	v_pk_mul_f32 v[146:147], v[160:161], v[160:161]
	v_pk_mul_f32 v[148:149], v[158:159], v[158:159]
	s_nop 0
	v_pk_mov_b32 v[150:151], v[148:149], v[146:147] op_sel:[1,0]
	v_mov_b32_e32 v149, v147
	v_pk_add_f32 v[146:147], v[150:151], v[148:149]
	v_pk_mul_f32 v[148:149], v[30:31], v[30:31]
	v_pk_add_f32 v[146:147], v[146:147], v[146:147] op_sel_hi:[0,1]
	v_pk_mul_f32 v[150:151], v[32:33], v[32:33]
	v_mul_f32_e32 v146, v28, v28
	v_pk_mov_b32 v[152:153], v[150:151], v[148:149] op_sel:[1,0]
	v_mov_b32_e32 v151, v149
	v_pk_add_f32 v[148:149], v[152:153], v[150:151]
	v_pk_fma_f32 v[150:151], v[28:29], v[28:29], v[146:147] op_sel_hi:[1,1,0]
	v_mul_f32_e32 v146, v22, v22
	v_pk_add_f32 v[148:149], v[148:149], v[148:149] op_sel_hi:[0,1]
	v_pk_fma_f32 v[152:153], v[22:23], v[22:23], v[146:147] op_sel_hi:[1,1,0]
	v_mul_f32_e32 v150, v20, v20
	v_mul_f32_e32 v152, v21, v21
	v_mul_f32_e32 v146, v18, v18
	v_mul_f32_e32 v148, v19, v19
	v_pk_add_f32 v[150:151], v[150:151], v[152:153]
	v_pk_add_f32 v[146:147], v[146:147], v[148:149]
	s_nop 0
	v_pk_add_f32 v[146:147], v[150:151], v[146:147]
	s_nop 0
	v_add_f32_e32 v27, v146, v147
	v_and_b32_e32 v147, 64, v193
	v_xor_b32_e32 v146, 16, v193
	v_add_u32_e32 v147, 64, v147
	v_cmp_lt_i32_e32 vcc, v146, v147
	s_nop 1
	v_cndmask_b32_e32 v146, v193, v146, vcc
	v_lshlrev_b32_e32 v146, 2, v146
	v_mov_b32_e32 v146, v27
	s_nop 1
	v_permlane16_swap_b32_e32 v27, v146
	v_add_f32_e32 v27, v27, v146
	v_xor_b32_e32 v146, 32, v193
	v_cmp_lt_i32_e32 vcc, v146, v147
	s_nop 1
	v_cndmask_b32_e32 v146, v193, v146, vcc
	v_lshlrev_b32_e32 v146, 2, v146
	v_mov_b32_e32 v146, v27
	s_nop 1
	v_permlane32_swap_b32_e32 v27, v146
	v_add_f32_e32 v27, v27, v146
	v_fmamk_f32 v27, v27, 0x3c800000, v192
	v_rsq_f32_e32 v152, v27
.LBB0_763:
	s_lshl_b32 s17, s22, 8
	v_pk_mul_f32 v[146:147], v[160:161], v[152:153] op_sel_hi:[1,0]
	v_pk_mul_f32 v[148:149], v[158:159], v[152:153] op_sel_hi:[1,0]
	v_pk_mul_f32 v[30:31], v[30:31], v[152:153] op_sel_hi:[1,0]
	v_pk_mul_f32 v[32:33], v[32:33], v[152:153] op_sel_hi:[1,0]
	s_or_b32 s26, s17, s46
	v_pk_mul_f32 v[150:151], v[6:7], v[148:149]
	v_pk_mul_f32 v[148:149], v[8:9], v[146:147]
	v_pk_mul_f32 v[146:147], v[2:3], v[32:33]
	v_pk_mul_f32 v[32:33], v[4:5], v[30:31]
	v_mov_b64_e32 v[30:31], s[58:59]
	s_ashr_i32 s27, s26, 31
	v_mad_i64_i32 v[30:31], s[28:29], v178, s51, v[30:31]
	v_lshl_add_u64 v[30:31], s[26:27], 1, v[30:31]
	v_pk_mul_f32 v[22:23], v[22:23], v[152:153] op_sel_hi:[1,0]
	v_pk_mul_f32 v[28:29], v[28:29], v[152:153] op_sel_hi:[1,0]
	v_pk_mul_f32 v[18:19], v[18:19], v[152:153] op_sel_hi:[1,0]
	v_pk_mul_f32 v[20:21], v[20:21], v[152:153] op_sel_hi:[1,0]
	v_cvt_pk_f16_f32 v154, v150, v151
	v_cvt_pk_f16_f32 v155, v148, v149
	v_cvt_pk_f16_f32 v156, v146, v147
	v_cvt_pk_f16_f32 v157, v32, v33
	v_lshl_add_u64 v[30:31], v[24:25], 1, v[30:31]
	v_pk_mul_f32 v[28:29], v[14:15], v[28:29]
	v_pk_mul_f32 v[22:23], v[16:17], v[22:23]
	v_pk_mul_f32 v[20:21], v[10:11], v[20:21]
	v_pk_mul_f32 v[18:19], v[12:13], v[18:19]
	global_store_dwordx4 v[30:31], v[154:157], off
	v_cvt_pk_f16_f32 v152, v28, v29
	v_cvt_pk_f16_f32 v153, v22, v23
	v_cvt_pk_f16_f32 v154, v20, v21
	v_cvt_pk_f16_f32 v155, v18, v19
	global_store_dwordx4 v[30:31], v[152:155], off offset:64
	global_load_dword v27, v[180:181], off offset:64
	s_and_b64 vcc, exec, s[2:3]
	s_waitcnt vmcnt(0)
	v_fmamk_f32 v27, v27, 0x3a800000, v192
	v_rsq_f32_e32 v27, v27
	s_nop 0
	v_mul_f32_e32 v184, 0x39800000, v27
	v_pk_mul_f32 v[158:159], v[144:145], v[184:185] op_sel_hi:[1,0]
	v_pk_mul_f32 v[160:161], v[142:143], v[184:185] op_sel_hi:[1,0]
	v_pk_mul_f32 v[154:155], v[140:141], v[184:185] op_sel_hi:[1,0]
	v_pk_mul_f32 v[156:157], v[138:139], v[184:185] op_sel_hi:[1,0]
	v_pk_mul_f32 v[144:145], v[136:137], v[184:185] op_sel_hi:[1,0]
	v_pk_mul_f32 v[152:153], v[134:135], v[184:185] op_sel_hi:[1,0]
	v_pk_mul_f32 v[30:31], v[132:133], v[184:185] op_sel_hi:[1,0]
	v_pk_mul_f32 v[142:143], v[130:131], v[184:185] op_sel_hi:[1,0]
	s_cbranch_vccnz .LBB0_765
	v_pk_mul_f32 v[26:27], v[158:159], v[158:159]
	v_pk_mul_f32 v[130:131], v[160:161], v[160:161]
	s_nop 0
	v_pk_mov_b32 v[132:133], v[130:131], v[26:27] op_sel:[1,0]
	v_mov_b32_e32 v131, v27
	v_pk_add_f32 v[26:27], v[132:133], v[130:131]
	v_pk_mul_f32 v[130:131], v[154:155], v[154:155]
	v_pk_add_f32 v[26:27], v[26:27], v[26:27] op_sel_hi:[0,1]
	v_pk_mul_f32 v[132:133], v[156:157], v[156:157]
	v_mul_f32_e32 v26, v152, v152
	v_pk_mov_b32 v[134:135], v[132:133], v[130:131] op_sel:[1,0]
	v_mov_b32_e32 v133, v131
	v_pk_add_f32 v[130:131], v[134:135], v[132:133]
	v_pk_fma_f32 v[132:133], v[152:153], v[152:153], v[26:27] op_sel_hi:[1,1,0]
	v_mul_f32_e32 v26, v144, v144
	v_pk_add_f32 v[130:131], v[130:131], v[130:131] op_sel_hi:[0,1]
	v_pk_fma_f32 v[134:135], v[144:145], v[144:145], v[26:27] op_sel_hi:[1,1,0]
	v_mul_f32_e32 v132, v142, v142
	v_mul_f32_e32 v134, v143, v143
	v_mul_f32_e32 v26, v30, v30
	v_mul_f32_e32 v130, v31, v31
	v_pk_add_f32 v[132:133], v[132:133], v[134:135]
	v_pk_add_f32 v[26:27], v[26:27], v[130:131]
	v_and_b32_e32 v130, 64, v193
	v_pk_add_f32 v[26:27], v[132:133], v[26:27]
	v_add_u32_e32 v130, 64, v130
	v_add_f32_e32 v26, v26, v27
	v_xor_b32_e32 v27, 16, v193
	v_cmp_lt_i32_e32 vcc, v27, v130
	s_nop 1
	v_cndmask_b32_e32 v27, v193, v27, vcc
	v_lshlrev_b32_e32 v27, 2, v27
	v_mov_b32_e32 v27, v26
	s_nop 1
	v_permlane16_swap_b32_e32 v26, v27
	v_add_f32_e32 v26, v26, v27
	v_xor_b32_e32 v27, 32, v193
	v_cmp_lt_i32_e32 vcc, v27, v130
	s_nop 1
	v_cndmask_b32_e32 v27, v193, v27, vcc
	v_lshlrev_b32_e32 v27, 2, v27
	v_mov_b32_e32 v27, v26
	s_nop 1
	v_permlane32_swap_b32_e32 v26, v27
	v_add_f32_e32 v26, v26, v27
	v_fmamk_f32 v26, v26, 0x3c800000, v192
	v_rsq_f32_e32 v26, v26
; __device__ __forceinline__ unsigned pkh(float lo, float hi) { f32x2 v = {lo, hi}; h16x2 h = __builtin_convertvector(v, h16x2); return __builtin_bit_cast(unsigned, h); }
;     __device__ __forceinline__ void operator()(f32x4 (&acc)[2][2][4][2], const Unit& u, const Order& S, int wr, int wc, int fr_, int fq_, LAS unsigned char*, int) const {
;     ...
;         for (int ai = 0; ai < 2; ++ai)
; #pragma unroll
;             for (int m = 0; m < 4; ++m) {
;                 const int row = row0 + ai * HALF + m * 16;
;                 const float sc = __builtin_amdgcn_rsqf(ss_in[row] * (1.0f / DM) + EPS) * pre;
;                 f32x4 v[2][2]; float sq = 0.f;
; #pragma unroll
;                 for (int bj = 0; bj < 2; ++bj)
; #pragma unroll
;                     for (int n = 0; n < 2; ++n) { v[bj][n] = acc[ai][bj][m][n] * sc; const f32x4 t = v[bj][n]; sq += (t[0] * t[0] + t[1] * t[1]) + (t[2] * t[2] + t[3] * t[3]); }
;                 float rn = 1.f;
;                 if (nrm) { sq += __shfl_xor(sq, 16); sq += __shfl_xor(sq, 32); rn = __builtin_amdgcn_rsqf(sq * (1.0f / HD) + EPS); }
; #pragma unroll
;                 for (int bj = 0; bj < 2; ++bj) {
;                     const f32x4 a = v[bj][0] * rn * gv[bj][0], b = v[bj][1] * rn * gv[bj][1];
;                     ks[bj][0] += a; ks[bj][1] += b;
;                     u32x4 w; w.x = pkh(a[0], a[1]); w.y = pkh(a[2], a[3]); w.z = pkh(b[0], b[1]); w.w = pkh(b[2], b[3]);
;                     *(u32x4*)(P + (size_t)row * NB + colh + 32 * bj + 8 * fq) = w;
;                 }
.LBB0_765:
	v_add_u32_e32 v27, 16, v178
	v_pk_mul_f32 v[130:131], v[158:159], v[26:27] op_sel_hi:[1,0]
	v_pk_mul_f32 v[132:133], v[160:161], v[26:27] op_sel_hi:[1,0]
	v_pk_mul_f32 v[138:139], v[8:9], v[130:131]
	v_pk_mul_f32 v[130:131], v[154:155], v[26:27] op_sel_hi:[1,0]
	v_mov_b64_e32 v[154:155], s[58:59]
	v_pk_mul_f32 v[140:141], v[6:7], v[132:133]
	v_pk_mul_f32 v[132:133], v[156:157], v[26:27] op_sel_hi:[1,0]
	v_mad_i64_i32 v[154:155], s[28:29], v27, s51, v[154:155]
	v_pk_mul_f32 v[134:135], v[4:5], v[130:131]
	v_pk_mul_f32 v[136:137], v[2:3], v[132:133]
	v_lshl_add_u64 v[154:155], s[26:27], 1, v[154:155]
	v_cvt_pk_f16_f32 v130, v140, v141
	v_cvt_pk_f16_f32 v131, v138, v139
	v_cvt_pk_f16_f32 v132, v136, v137
	v_cvt_pk_f16_f32 v133, v134, v135
	v_lshl_add_u64 v[154:155], v[24:25], 1, v[154:155]
	global_store_dwordx4 v[154:155], v[130:133], off
	v_pk_mul_f32 v[30:31], v[30:31], v[26:27] op_sel_hi:[1,0]
	v_pk_mul_f32 v[142:143], v[142:143], v[26:27] op_sel_hi:[1,0]
	v_pk_mul_f32 v[130:131], v[144:145], v[26:27] op_sel_hi:[1,0]
	v_pk_mul_f32 v[132:133], v[152:153], v[26:27] op_sel_hi:[1,0]
	v_pk_mul_f32 v[130:131], v[16:17], v[130:131]
	v_pk_mul_f32 v[132:133], v[14:15], v[132:133]
	v_pk_mul_f32 v[26:27], v[12:13], v[30:31]
	v_pk_mul_f32 v[30:31], v[10:11], v[142:143]
	v_cvt_pk_f16_f32 v142, v132, v133
	v_cvt_pk_f16_f32 v143, v130, v131
	v_cvt_pk_f16_f32 v144, v30, v31
	v_cvt_pk_f16_f32 v145, v26, v27
	global_store_dwordx4 v[154:155], v[142:145], off offset:64
	global_load_dword v142, v[180:181], off offset:128
	s_and_b64 vcc, exec, s[2:3]
	s_waitcnt vmcnt(0)
	v_fmamk_f32 v142, v142, 0x3a800000, v192
	v_rsq_f32_e32 v143, v142
	v_mov_b32_e32 v142, 1.0
	v_mul_f32_e32 v144, 0x39800000, v143
	v_pk_mul_f32 v[128:129], v[128:129], v[144:145] op_sel_hi:[1,0]
	v_pk_mul_f32 v[126:127], v[126:127], v[144:145] op_sel_hi:[1,0]
	v_pk_mul_f32 v[124:125], v[124:125], v[144:145] op_sel_hi:[1,0]
	v_pk_mul_f32 v[122:123], v[122:123], v[144:145] op_sel_hi:[1,0]
	v_pk_mul_f32 v[120:121], v[120:121], v[144:145] op_sel_hi:[1,0]
	v_pk_mul_f32 v[118:119], v[118:119], v[144:145] op_sel_hi:[1,0]
	v_pk_mul_f32 v[116:117], v[116:117], v[144:145] op_sel_hi:[1,0]
	v_pk_mul_f32 v[114:115], v[114:115], v[144:145] op_sel_hi:[1,0]
	v_mov_b32_e32 v144, 1.0
	s_cbranch_vccnz .LBB0_767
	v_pk_mul_f32 v[144:145], v[128:129], v[128:129]
	v_pk_mul_f32 v[152:153], v[126:127], v[126:127]
	s_nop 0
	v_pk_mov_b32 v[154:155], v[152:153], v[144:145] op_sel:[1,0]
	v_mov_b32_e32 v153, v145
	v_pk_add_f32 v[144:145], v[154:155], v[152:153]
	v_pk_mul_f32 v[152:153], v[124:125], v[124:125]
	v_pk_add_f32 v[144:145], v[144:145], v[144:145] op_sel_hi:[0,1]
	v_pk_mul_f32 v[154:155], v[122:123], v[122:123]
	v_mul_f32_e32 v144, v118, v118
	v_pk_mov_b32 v[156:157], v[154:155], v[152:153] op_sel:[1,0]
	v_mov_b32_e32 v155, v153
	v_pk_add_f32 v[152:153], v[156:157], v[154:155]
	v_pk_fma_f32 v[154:155], v[118:119], v[118:119], v[144:145] op_sel_hi:[1,1,0]
	v_mul_f32_e32 v144, v120, v120
	v_pk_add_f32 v[152:153], v[152:153], v[152:153] op_sel_hi:[0,1]
	v_pk_fma_f32 v[156:157], v[120:121], v[120:121], v[144:145] op_sel_hi:[1,1,0]
	v_mul_f32_e32 v154, v114, v114
	v_mul_f32_e32 v156, v115, v115
	v_mul_f32_e32 v144, v116, v116
	v_mul_f32_e32 v152, v117, v117
	v_pk_add_f32 v[154:155], v[154:155], v[156:157]
	v_pk_add_f32 v[144:145], v[144:145], v[152:153]
	s_nop 0
	v_pk_add_f32 v[144:145], v[154:155], v[144:145]
	s_nop 0
	v_add_f32_e32 v143, v144, v145
	v_and_b32_e32 v145, 64, v193
	v_xor_b32_e32 v144, 16, v193
	v_add_u32_e32 v145, 64, v145
	v_cmp_lt_i32_e32 vcc, v144, v145
	s_nop 1
	v_cndmask_b32_e32 v144, v193, v144, vcc
	v_lshlrev_b32_e32 v144, 2, v144
	v_mov_b32_e32 v144, v143
	s_nop 1
	v_permlane16_swap_b32_e32 v143, v144
	v_add_f32_e32 v143, v143, v144
	v_xor_b32_e32 v144, 32, v193
	v_cmp_lt_i32_e32 vcc, v144, v145
	s_nop 1
	v_cndmask_b32_e32 v144, v193, v144, vcc
	v_lshlrev_b32_e32 v144, 2, v144
	v_mov_b32_e32 v144, v143
	s_nop 1
	v_permlane32_swap_b32_e32 v143, v144
	v_add_f32_e32 v143, v143, v144
	v_fmamk_f32 v143, v143, 0x3c800000, v192
	v_rsq_f32_e32 v144, v143
.LBB0_767:
	v_add_u32_e32 v143, 32, v178
	v_pk_mul_f32 v[128:129], v[128:129], v[144:145] op_sel_hi:[1,0]
	v_pk_mul_f32 v[152:153], v[126:127], v[144:145] op_sel_hi:[1,0]
	v_mov_b64_e32 v[156:157], s[58:59]
	v_pk_mul_f32 v[126:127], v[8:9], v[128:129]
	v_pk_mul_f32 v[128:129], v[6:7], v[152:153]
	v_pk_mul_f32 v[124:125], v[124:125], v[144:145] op_sel_hi:[1,0]
	v_pk_mul_f32 v[152:153], v[122:123], v[144:145] op_sel_hi:[1,0]
	v_mad_i64_i32 v[156:157], s[28:29], v143, s51, v[156:157]
	v_pk_mul_f32 v[122:123], v[4:5], v[124:125]
	v_pk_mul_f32 v[124:125], v[2:3], v[152:153]
	v_lshl_add_u64 v[156:157], s[26:27], 1, v[156:157]
	v_cvt_pk_f16_f32 v152, v128, v129
	v_cvt_pk_f16_f32 v153, v126, v127
	v_cvt_pk_f16_f32 v154, v124, v125
	v_cvt_pk_f16_f32 v155, v122, v123
	v_lshl_add_u64 v[156:157], v[24:25], 1, v[156:157]
	global_store_dwordx4 v[156:157], v[152:155], off
	v_pk_mul_f32 v[120:121], v[120:121], v[144:145] op_sel_hi:[1,0]
	v_pk_mul_f32 v[116:117], v[116:117], v[144:145] op_sel_hi:[1,0]
	v_pk_mul_f32 v[152:153], v[118:119], v[144:145] op_sel_hi:[1,0]
	v_pk_mul_f32 v[144:145], v[114:115], v[144:145] op_sel_hi:[1,0]
	v_pk_mul_f32 v[118:119], v[16:17], v[120:121]
	v_pk_mul_f32 v[120:121], v[14:15], v[152:153]
	v_pk_mul_f32 v[114:115], v[12:13], v[116:117]
	v_pk_mul_f32 v[116:117], v[10:11], v[144:145]
	v_cvt_pk_f16_f32 v152, v120, v121
	v_cvt_pk_f16_f32 v153, v118, v119
	v_cvt_pk_f16_f32 v154, v116, v117
	v_cvt_pk_f16_f32 v155, v114, v115
	global_store_dwordx4 v[156:157], v[152:155], off offset:64
	global_load_dword v143, v[180:181], off offset:192
	s_and_b64 vcc, exec, s[2:3]
	s_waitcnt vmcnt(0)
	v_fmamk_f32 v143, v143, 0x3a800000, v192
	v_rsq_f32_e32 v143, v143
	s_nop 0
	v_mul_f32_e32 v144, 0x39800000, v143
	v_pk_mul_f32 v[112:113], v[112:113], v[144:145] op_sel_hi:[1,0]
	v_pk_mul_f32 v[110:111], v[110:111], v[144:145] op_sel_hi:[1,0]
	v_pk_mul_f32 v[108:109], v[108:109], v[144:145] op_sel_hi:[1,0]
	v_pk_mul_f32 v[106:107], v[106:107], v[144:145] op_sel_hi:[1,0]
	v_pk_mul_f32 v[104:105], v[104:105], v[144:145] op_sel_hi:[1,0]
	v_pk_mul_f32 v[102:103], v[102:103], v[144:145] op_sel_hi:[1,0]
	v_pk_mul_f32 v[100:101], v[100:101], v[144:145] op_sel_hi:[1,0]
	v_pk_mul_f32 v[98:99], v[98:99], v[144:145] op_sel_hi:[1,0]
	s_cbranch_vccnz .LBB0_769
; __device__ __forceinline__ unsigned pkh(float lo, float hi) { f32x2 v = {lo, hi}; h16x2 h = __builtin_convertvector(v, h16x2); return __builtin_bit_cast(unsigned, h); }
;     __device__ __forceinline__ void operator()(f32x4 (&acc)[2][2][4][2], const Unit& u, const Order& S, int wr, int wc, int fr_, int fq_, LAS unsigned char*, int) const {
;     ...
;         for (int ai = 0; ai < 2; ++ai)
; #pragma unroll
;             for (int m = 0; m < 4; ++m) {
;                 const int row = row0 + ai * HALF + m * 16;
;                 const float sc = __builtin_amdgcn_rsqf(ss_in[row] * (1.0f / DM) + EPS) * pre;
;                 f32x4 v[2][2]; float sq = 0.f;
; #pragma unroll
;                 for (int bj = 0; bj < 2; ++bj)
; #pragma unroll
;                     for (int n = 0; n < 2; ++n) { v[bj][n] = acc[ai][bj][m][n] * sc; const f32x4 t = v[bj][n]; sq += (t[0] * t[0] + t[1] * t[1]) + (t[2] * t[2] + t[3] * t[3]); }
;                 float rn = 1.f;
;                 if (nrm) { sq += __shfl_xor(sq, 16); sq += __shfl_xor(sq, 32); rn = __builtin_amdgcn_rsqf(sq * (1.0f / HD) + EPS); }
; #pragma unroll
;                 for (int bj = 0; bj < 2; ++bj) {
;                     const f32x4 a = v[bj][0] * rn * gv[bj][0], b = v[bj][1] * rn * gv[bj][1];
;                     ks[bj][0] += a; ks[bj][1] += b;
;                     u32x4 w; w.x = pkh(a[0], a[1]); w.y = pkh(a[2], a[3]); w.z = pkh(b[0], b[1]); w.w = pkh(b[2], b[3]);
;                     *(u32x4*)(P + (size_t)row * NB + colh + 32 * bj + 8 * fq) = w;
;                 }
	v_pk_mul_f32 v[142:143], v[112:113], v[112:113]
	v_pk_mul_f32 v[144:145], v[110:111], v[110:111]
	s_nop 0
	v_pk_mov_b32 v[152:153], v[144:145], v[142:143] op_sel:[1,0]
	v_mov_b32_e32 v145, v143
	v_pk_add_f32 v[142:143], v[152:153], v[144:145]
	v_pk_mul_f32 v[144:145], v[108:109], v[108:109]
	v_pk_add_f32 v[142:143], v[142:143], v[142:143] op_sel_hi:[0,1]
	v_pk_mul_f32 v[152:153], v[106:107], v[106:107]
	v_mul_f32_e32 v142, v102, v102
	v_pk_mov_b32 v[154:155], v[152:153], v[144:145] op_sel:[1,0]
	v_mov_b32_e32 v153, v145
	v_pk_add_f32 v[144:145], v[154:155], v[152:153]
	v_pk_fma_f32 v[152:153], v[102:103], v[102:103], v[142:143] op_sel_hi:[1,1,0]
	v_mul_f32_e32 v142, v104, v104
	v_pk_add_f32 v[144:145], v[144:145], v[144:145] op_sel_hi:[0,1]
	v_pk_fma_f32 v[154:155], v[104:105], v[104:105], v[142:143] op_sel_hi:[1,1,0]
	v_mul_f32_e32 v152, v98, v98
	v_mul_f32_e32 v154, v99, v99
	v_mul_f32_e32 v142, v100, v100
	v_mul_f32_e32 v144, v101, v101
	v_pk_add_f32 v[152:153], v[152:153], v[154:155]
	v_pk_add_f32 v[142:143], v[142:143], v[144:145]
	v_and_b32_e32 v144, 64, v193
	v_pk_add_f32 v[142:143], v[152:153], v[142:143]
	v_add_u32_e32 v144, 64, v144
	v_add_f32_e32 v142, v142, v143
	v_xor_b32_e32 v143, 16, v193
	v_cmp_lt_i32_e32 vcc, v143, v144
	s_nop 1
	v_cndmask_b32_e32 v143, v193, v143, vcc
	v_lshlrev_b32_e32 v143, 2, v143
	v_mov_b32_e32 v143, v142
	s_nop 1
	v_permlane16_swap_b32_e32 v142, v143
	v_add_f32_e32 v142, v142, v143
	v_xor_b32_e32 v143, 32, v193
	v_cmp_lt_i32_e32 vcc, v143, v144
	s_nop 1
	v_cndmask_b32_e32 v143, v193, v143, vcc
	v_lshlrev_b32_e32 v143, 2, v143
	v_mov_b32_e32 v143, v142
	s_nop 1
	v_permlane32_swap_b32_e32 v142, v143
	v_add_f32_e32 v142, v142, v143
	v_fmamk_f32 v142, v142, 0x3c800000, v192
	v_rsq_f32_e32 v142, v142
.LBB0_769:
	v_add_u32_e32 v143, 48, v178
	v_pk_mul_f32 v[112:113], v[112:113], v[142:143] op_sel_hi:[1,0]
	v_pk_mul_f32 v[144:145], v[110:111], v[142:143] op_sel_hi:[1,0]
	v_pk_mul_f32 v[110:111], v[8:9], v[112:113]
	v_pk_mul_f32 v[112:113], v[6:7], v[144:145]
	v_pk_mul_f32 v[108:109], v[108:109], v[142:143] op_sel_hi:[1,0]
	v_pk_mul_f32 v[144:145], v[106:107], v[142:143] op_sel_hi:[1,0]
	v_pk_mul_f32 v[106:107], v[4:5], v[108:109]
	v_pk_mul_f32 v[108:109], v[2:3], v[144:145]
	v_mov_b64_e32 v[144:145], s[58:59]
	v_mad_i64_i32 v[144:145], s[28:29], v143, s51, v[144:145]
	v_lshl_add_u64 v[144:145], s[26:27], 1, v[144:145]
	v_lshl_add_u64 v[156:157], v[24:25], 1, v[144:145]
	v_pk_mul_f32 v[104:105], v[104:105], v[142:143] op_sel_hi:[1,0]
	v_pk_mul_f32 v[144:145], v[102:103], v[142:143] op_sel_hi:[1,0]
	v_pk_mul_f32 v[100:101], v[100:101], v[142:143] op_sel_hi:[1,0]
	v_pk_mul_f32 v[142:143], v[98:99], v[142:143] op_sel_hi:[1,0]
	v_pk_mul_f32 v[102:103], v[16:17], v[104:105]
	v_pk_mul_f32 v[104:105], v[14:15], v[144:145]
	v_pk_mul_f32 v[98:99], v[12:13], v[100:101]
	v_pk_mul_f32 v[100:101], v[10:11], v[142:143]
	v_cvt_pk_f16_f32 v152, v112, v113
	v_cvt_pk_f16_f32 v153, v110, v111
	v_cvt_pk_f16_f32 v154, v108, v109
	v_cvt_pk_f16_f32 v155, v106, v107
	v_cvt_pk_f16_f32 v142, v104, v105
	v_cvt_pk_f16_f32 v143, v102, v103
	v_cvt_pk_f16_f32 v144, v100, v101
	v_cvt_pk_f16_f32 v145, v98, v99
	global_store_dwordx4 v[156:157], v[152:155], off
	global_store_dwordx4 v[156:157], v[142:145], off offset:64
	global_load_dword v142, v[180:181], off offset:512
	s_and_b64 vcc, exec, s[2:3]
	s_waitcnt vmcnt(0)
	v_fmamk_f32 v142, v142, 0x3a800000, v192
	v_rsq_f32_e32 v143, v142
	v_mov_b32_e32 v142, 1.0
	v_mul_f32_e32 v144, 0x39800000, v143
	v_pk_mul_f32 v[96:97], v[96:97], v[144:145] op_sel_hi:[1,0]
	v_pk_mul_f32 v[94:95], v[94:95], v[144:145] op_sel_hi:[1,0]
	v_pk_mul_f32 v[92:93], v[92:93], v[144:145] op_sel_hi:[1,0]
	v_pk_mul_f32 v[90:91], v[90:91], v[144:145] op_sel_hi:[1,0]
	v_pk_mul_f32 v[88:89], v[88:89], v[144:145] op_sel_hi:[1,0]
	v_pk_mul_f32 v[86:87], v[86:87], v[144:145] op_sel_hi:[1,0]
	v_pk_mul_f32 v[84:85], v[84:85], v[144:145] op_sel_hi:[1,0]
	v_pk_mul_f32 v[82:83], v[82:83], v[144:145] op_sel_hi:[1,0]
	v_mov_b32_e32 v144, 1.0
	s_cbranch_vccnz .LBB0_771
	v_pk_mul_f32 v[144:145], v[96:97], v[96:97]
	v_pk_mul_f32 v[152:153], v[94:95], v[94:95]
	s_nop 0
	v_pk_mov_b32 v[154:155], v[152:153], v[144:145] op_sel:[1,0]
	v_mov_b32_e32 v153, v145
	v_pk_add_f32 v[144:145], v[154:155], v[152:153]
	v_pk_mul_f32 v[152:153], v[92:93], v[92:93]
	v_pk_add_f32 v[144:145], v[144:145], v[144:145] op_sel_hi:[0,1]
	v_pk_mul_f32 v[154:155], v[90:91], v[90:91]
	v_mul_f32_e32 v144, v86, v86
	v_pk_mov_b32 v[156:157], v[154:155], v[152:153] op_sel:[1,0]
	v_mov_b32_e32 v155, v153
	v_pk_add_f32 v[152:153], v[156:157], v[154:155]
	v_pk_fma_f32 v[154:155], v[86:87], v[86:87], v[144:145] op_sel_hi:[1,1,0]
	v_mul_f32_e32 v144, v88, v88
	v_pk_add_f32 v[152:153], v[152:153], v[152:153] op_sel_hi:[0,1]
	v_pk_fma_f32 v[156:157], v[88:89], v[88:89], v[144:145] op_sel_hi:[1,1,0]
	v_mul_f32_e32 v154, v82, v82
	v_mul_f32_e32 v156, v83, v83
	v_mul_f32_e32 v144, v84, v84
	v_mul_f32_e32 v152, v85, v85
	v_pk_add_f32 v[154:155], v[154:155], v[156:157]
	v_pk_add_f32 v[144:145], v[144:145], v[152:153]
	s_nop 0
	v_pk_add_f32 v[144:145], v[154:155], v[144:145]
	s_nop 0
	v_add_f32_e32 v143, v144, v145
	v_and_b32_e32 v145, 64, v193
	v_xor_b32_e32 v144, 16, v193
	v_add_u32_e32 v145, 64, v145
	v_cmp_lt_i32_e32 vcc, v144, v145
	s_nop 1
	v_cndmask_b32_e32 v144, v193, v144, vcc
	v_lshlrev_b32_e32 v144, 2, v144
	v_mov_b32_e32 v144, v143
	s_nop 1
	v_permlane16_swap_b32_e32 v143, v144
	v_add_f32_e32 v143, v143, v144
	v_xor_b32_e32 v144, 32, v193
	v_cmp_lt_i32_e32 vcc, v144, v145
	s_nop 1
	v_cndmask_b32_e32 v144, v193, v144, vcc
	v_lshlrev_b32_e32 v144, 2, v144
	v_mov_b32_e32 v144, v143
	s_nop 1
	v_permlane32_swap_b32_e32 v143, v144
	v_add_f32_e32 v143, v143, v144
	v_fmamk_f32 v143, v143, 0x3c800000, v192
	v_rsq_f32_e32 v144, v143
; __device__ __forceinline__ unsigned pkh(float lo, float hi) { f32x2 v = {lo, hi}; h16x2 h = __builtin_convertvector(v, h16x2); return __builtin_bit_cast(unsigned, h); }
;     __device__ __forceinline__ void operator()(f32x4 (&acc)[2][2][4][2], const Unit& u, const Order& S, int wr, int wc, int fr_, int fq_, LAS unsigned char*, int) const {
;     ...
;         for (int ai = 0; ai < 2; ++ai)
; #pragma unroll
;             for (int m = 0; m < 4; ++m) {
;                 const int row = row0 + ai * HALF + m * 16;
;                 const float sc = __builtin_amdgcn_rsqf(ss_in[row] * (1.0f / DM) + EPS) * pre;
;                 f32x4 v[2][2]; float sq = 0.f;
; #pragma unroll
;                 for (int bj = 0; bj < 2; ++bj)
; #pragma unroll
;                     for (int n = 0; n < 2; ++n) { v[bj][n] = acc[ai][bj][m][n] * sc; const f32x4 t = v[bj][n]; sq += (t[0] * t[0] + t[1] * t[1]) + (t[2] * t[2] + t[3] * t[3]); }
;                 float rn = 1.f;
;                 if (nrm) { sq += __shfl_xor(sq, 16); sq += __shfl_xor(sq, 32); rn = __builtin_amdgcn_rsqf(sq * (1.0f / HD) + EPS); }
; #pragma unroll
;                 for (int bj = 0; bj < 2; ++bj) {
;                     const f32x4 a = v[bj][0] * rn * gv[bj][0], b = v[bj][1] * rn * gv[bj][1];
;                     ks[bj][0] += a; ks[bj][1] += b;
;                     u32x4 w; w.x = pkh(a[0], a[1]); w.y = pkh(a[2], a[3]); w.z = pkh(b[0], b[1]); w.w = pkh(b[2], b[3]);
;                     *(u32x4*)(P + (size_t)row * NB + colh + 32 * bj + 8 * fq) = w;
;                 }
.LBB0_771:
	v_add_u32_e32 v143, 0x80, v178
	v_pk_mul_f32 v[96:97], v[96:97], v[144:145] op_sel_hi:[1,0]
	v_pk_mul_f32 v[152:153], v[94:95], v[144:145] op_sel_hi:[1,0]
	v_mov_b64_e32 v[156:157], s[58:59]
	v_pk_mul_f32 v[94:95], v[8:9], v[96:97]
	v_pk_mul_f32 v[96:97], v[6:7], v[152:153]
	v_pk_mul_f32 v[92:93], v[92:93], v[144:145] op_sel_hi:[1,0]
	v_pk_mul_f32 v[152:153], v[90:91], v[144:145] op_sel_hi:[1,0]
	v_mad_i64_i32 v[156:157], s[28:29], v143, s51, v[156:157]
	v_pk_mul_f32 v[90:91], v[4:5], v[92:93]
	v_pk_mul_f32 v[92:93], v[2:3], v[152:153]
	v_lshl_add_u64 v[156:157], s[26:27], 1, v[156:157]
	v_cvt_pk_f16_f32 v152, v96, v97
	v_cvt_pk_f16_f32 v153, v94, v95
	v_cvt_pk_f16_f32 v154, v92, v93
	v_cvt_pk_f16_f32 v155, v90, v91
	v_lshl_add_u64 v[156:157], v[24:25], 1, v[156:157]
	global_store_dwordx4 v[156:157], v[152:155], off
	v_pk_mul_f32 v[88:89], v[88:89], v[144:145] op_sel_hi:[1,0]
	v_pk_mul_f32 v[84:85], v[84:85], v[144:145] op_sel_hi:[1,0]
	v_pk_mul_f32 v[152:153], v[86:87], v[144:145] op_sel_hi:[1,0]
	v_pk_mul_f32 v[144:145], v[82:83], v[144:145] op_sel_hi:[1,0]
	v_pk_mul_f32 v[86:87], v[16:17], v[88:89]
	v_pk_mul_f32 v[88:89], v[14:15], v[152:153]
	v_pk_mul_f32 v[82:83], v[12:13], v[84:85]
	v_pk_mul_f32 v[84:85], v[10:11], v[144:145]
	v_cvt_pk_f16_f32 v152, v88, v89
	v_cvt_pk_f16_f32 v153, v86, v87
	v_cvt_pk_f16_f32 v154, v84, v85
	v_cvt_pk_f16_f32 v155, v82, v83
	global_store_dwordx4 v[156:157], v[152:155], off offset:64
	global_load_dword v143, v[180:181], off offset:576
	s_and_b64 vcc, exec, s[2:3]
	s_waitcnt vmcnt(0)
	v_fmamk_f32 v143, v143, 0x3a800000, v192
	v_rsq_f32_e32 v143, v143
	s_nop 0
	v_mul_f32_e32 v144, 0x39800000, v143
	v_pk_mul_f32 v[80:81], v[80:81], v[144:145] op_sel_hi:[1,0]
	v_pk_mul_f32 v[78:79], v[78:79], v[144:145] op_sel_hi:[1,0]
	v_pk_mul_f32 v[76:77], v[76:77], v[144:145] op_sel_hi:[1,0]
	v_pk_mul_f32 v[74:75], v[74:75], v[144:145] op_sel_hi:[1,0]
	v_pk_mul_f32 v[72:73], v[72:73], v[144:145] op_sel_hi:[1,0]
	v_pk_mul_f32 v[70:71], v[70:71], v[144:145] op_sel_hi:[1,0]
	v_pk_mul_f32 v[68:69], v[68:69], v[144:145] op_sel_hi:[1,0]
	v_pk_mul_f32 v[66:67], v[66:67], v[144:145] op_sel_hi:[1,0]
	s_cbranch_vccnz .LBB0_773
	v_pk_mul_f32 v[142:143], v[80:81], v[80:81]
	v_pk_mul_f32 v[144:145], v[78:79], v[78:79]
	s_nop 0
	v_pk_mov_b32 v[152:153], v[144:145], v[142:143] op_sel:[1,0]
	v_mov_b32_e32 v145, v143
	v_pk_add_f32 v[142:143], v[152:153], v[144:145]
	v_pk_mul_f32 v[144:145], v[76:77], v[76:77]
	v_pk_add_f32 v[142:143], v[142:143], v[142:143] op_sel_hi:[0,1]
	v_pk_mul_f32 v[152:153], v[74:75], v[74:75]
	v_mul_f32_e32 v142, v70, v70
	v_pk_mov_b32 v[154:155], v[152:153], v[144:145] op_sel:[1,0]
	v_mov_b32_e32 v153, v145
	v_pk_add_f32 v[144:145], v[154:155], v[152:153]
	v_pk_fma_f32 v[152:153], v[70:71], v[70:71], v[142:143] op_sel_hi:[1,1,0]
	v_mul_f32_e32 v142, v72, v72
	v_pk_add_f32 v[144:145], v[144:145], v[144:145] op_sel_hi:[0,1]
	v_pk_fma_f32 v[154:155], v[72:73], v[72:73], v[142:143] op_sel_hi:[1,1,0]
	v_mul_f32_e32 v152, v66, v66
	v_mul_f32_e32 v154, v67, v67
	v_mul_f32_e32 v142, v68, v68
	v_mul_f32_e32 v144, v69, v69
	v_pk_add_f32 v[152:153], v[152:153], v[154:155]
	v_pk_add_f32 v[142:143], v[142:143], v[144:145]
	v_and_b32_e32 v144, 64, v193
	v_pk_add_f32 v[142:143], v[152:153], v[142:143]
	v_add_u32_e32 v144, 64, v144
	v_add_f32_e32 v142, v142, v143
	v_xor_b32_e32 v143, 16, v193
	v_cmp_lt_i32_e32 vcc, v143, v144
	s_nop 1
	v_cndmask_b32_e32 v143, v193, v143, vcc
	v_lshlrev_b32_e32 v143, 2, v143
	v_mov_b32_e32 v143, v142
	s_nop 1
	v_permlane16_swap_b32_e32 v142, v143
	v_add_f32_e32 v142, v142, v143
	v_xor_b32_e32 v143, 32, v193
	v_cmp_lt_i32_e32 vcc, v143, v144
	s_nop 1
	v_cndmask_b32_e32 v143, v193, v143, vcc
	v_lshlrev_b32_e32 v143, 2, v143
	v_mov_b32_e32 v143, v142
	s_nop 1
	v_permlane32_swap_b32_e32 v142, v143
	v_add_f32_e32 v142, v142, v143
	v_fmamk_f32 v142, v142, 0x3c800000, v192
	v_rsq_f32_e32 v142, v142
.LBB0_773:
	v_add_u32_e32 v143, 0x90, v178
	v_pk_mul_f32 v[80:81], v[80:81], v[142:143] op_sel_hi:[1,0]
	v_pk_mul_f32 v[144:145], v[78:79], v[142:143] op_sel_hi:[1,0]
	v_pk_mul_f32 v[78:79], v[8:9], v[80:81]
	v_pk_mul_f32 v[80:81], v[6:7], v[144:145]
	v_pk_mul_f32 v[76:77], v[76:77], v[142:143] op_sel_hi:[1,0]
	v_pk_mul_f32 v[144:145], v[74:75], v[142:143] op_sel_hi:[1,0]
	v_pk_mul_f32 v[74:75], v[4:5], v[76:77]
	v_pk_mul_f32 v[76:77], v[2:3], v[144:145]
	v_mov_b64_e32 v[144:145], s[58:59]
	v_mad_i64_i32 v[144:145], s[28:29], v143, s51, v[144:145]
	v_lshl_add_u64 v[144:145], s[26:27], 1, v[144:145]
	v_lshl_add_u64 v[156:157], v[24:25], 1, v[144:145]
	v_pk_mul_f32 v[72:73], v[72:73], v[142:143] op_sel_hi:[1,0]
	v_pk_mul_f32 v[144:145], v[70:71], v[142:143] op_sel_hi:[1,0]
	v_pk_mul_f32 v[68:69], v[68:69], v[142:143] op_sel_hi:[1,0]
	v_pk_mul_f32 v[142:143], v[66:67], v[142:143] op_sel_hi:[1,0]
	v_pk_mul_f32 v[70:71], v[16:17], v[72:73]
	v_pk_mul_f32 v[72:73], v[14:15], v[144:145]
	v_pk_mul_f32 v[66:67], v[12:13], v[68:69]
	v_pk_mul_f32 v[68:69], v[10:11], v[142:143]
	v_cvt_pk_f16_f32 v152, v80, v81
	v_cvt_pk_f16_f32 v153, v78, v79
	v_cvt_pk_f16_f32 v154, v76, v77
	v_cvt_pk_f16_f32 v155, v74, v75
	v_cvt_pk_f16_f32 v142, v72, v73
	v_cvt_pk_f16_f32 v143, v70, v71
	v_cvt_pk_f16_f32 v144, v68, v69
	v_cvt_pk_f16_f32 v145, v66, v67
	global_store_dwordx4 v[156:157], v[152:155], off
	global_store_dwordx4 v[156:157], v[142:145], off offset:64
	global_load_dword v142, v[180:181], off offset:640
	s_and_b64 vcc, exec, s[2:3]
	s_waitcnt vmcnt(0)
	v_fmamk_f32 v142, v142, 0x3a800000, v192
	v_rsq_f32_e32 v143, v142
	v_mov_b32_e32 v142, 1.0
	v_mul_f32_e32 v144, 0x39800000, v143
	v_pk_mul_f32 v[64:65], v[64:65], v[144:145] op_sel_hi:[1,0]
	v_pk_mul_f32 v[62:63], v[62:63], v[144:145] op_sel_hi:[1,0]
	v_pk_mul_f32 v[60:61], v[60:61], v[144:145] op_sel_hi:[1,0]
	v_pk_mul_f32 v[58:59], v[58:59], v[144:145] op_sel_hi:[1,0]
	v_pk_mul_f32 v[56:57], v[56:57], v[144:145] op_sel_hi:[1,0]
	v_pk_mul_f32 v[54:55], v[54:55], v[144:145] op_sel_hi:[1,0]
	v_pk_mul_f32 v[52:53], v[52:53], v[144:145] op_sel_hi:[1,0]
	v_pk_mul_f32 v[50:51], v[50:51], v[144:145] op_sel_hi:[1,0]
	v_mov_b32_e32 v144, 1.0
	s_cbranch_vccnz .LBB0_775
; __device__ __forceinline__ unsigned pkh(float lo, float hi) { f32x2 v = {lo, hi}; h16x2 h = __builtin_convertvector(v, h16x2); return __builtin_bit_cast(unsigned, h); }
;     __device__ __forceinline__ void operator()(f32x4 (&acc)[2][2][4][2], const Unit& u, const Order& S, int wr, int wc, int fr_, int fq_, LAS unsigned char*, int) const {
;     ...
;         for (int ai = 0; ai < 2; ++ai)
; #pragma unroll
;             for (int m = 0; m < 4; ++m) {
;                 const int row = row0 + ai * HALF + m * 16;
;                 const float sc = __builtin_amdgcn_rsqf(ss_in[row] * (1.0f / DM) + EPS) * pre;
;                 f32x4 v[2][2]; float sq = 0.f;
; #pragma unroll
;                 for (int bj = 0; bj < 2; ++bj)
; #pragma unroll
;                     for (int n = 0; n < 2; ++n) { v[bj][n] = acc[ai][bj][m][n] * sc; const f32x4 t = v[bj][n]; sq += (t[0] * t[0] + t[1] * t[1]) + (t[2] * t[2] + t[3] * t[3]); }
;                 float rn = 1.f;
;                 if (nrm) { sq += __shfl_xor(sq, 16); sq += __shfl_xor(sq, 32); rn = __builtin_amdgcn_rsqf(sq * (1.0f / HD) + EPS); }
; #pragma unroll
;                 for (int bj = 0; bj < 2; ++bj) {
;                     const f32x4 a = v[bj][0] * rn * gv[bj][0], b = v[bj][1] * rn * gv[bj][1];
;                     ks[bj][0] += a; ks[bj][1] += b;
;                     u32x4 w; w.x = pkh(a[0], a[1]); w.y = pkh(a[2], a[3]); w.z = pkh(b[0], b[1]); w.w = pkh(b[2], b[3]);
;                     *(u32x4*)(P + (size_t)row * NB + colh + 32 * bj + 8 * fq) = w;
;                 }
	v_pk_mul_f32 v[144:145], v[64:65], v[64:65]
	v_pk_mul_f32 v[152:153], v[62:63], v[62:63]
	s_nop 0
	v_pk_mov_b32 v[154:155], v[152:153], v[144:145] op_sel:[1,0]
	v_mov_b32_e32 v153, v145
	v_pk_add_f32 v[144:145], v[154:155], v[152:153]
	v_pk_mul_f32 v[152:153], v[60:61], v[60:61]
	v_pk_add_f32 v[144:145], v[144:145], v[144:145] op_sel_hi:[0,1]
	v_pk_mul_f32 v[154:155], v[58:59], v[58:59]
	v_mul_f32_e32 v144, v54, v54
	v_pk_mov_b32 v[156:157], v[154:155], v[152:153] op_sel:[1,0]
	v_mov_b32_e32 v155, v153
	v_pk_add_f32 v[152:153], v[156:157], v[154:155]
	v_pk_fma_f32 v[154:155], v[54:55], v[54:55], v[144:145] op_sel_hi:[1,1,0]
	v_mul_f32_e32 v144, v56, v56
	v_pk_add_f32 v[152:153], v[152:153], v[152:153] op_sel_hi:[0,1]
	v_pk_fma_f32 v[156:157], v[56:57], v[56:57], v[144:145] op_sel_hi:[1,1,0]
	v_mul_f32_e32 v154, v50, v50
	v_mul_f32_e32 v156, v51, v51
	v_mul_f32_e32 v144, v52, v52
	v_mul_f32_e32 v152, v53, v53
	v_pk_add_f32 v[154:155], v[154:155], v[156:157]
	v_pk_add_f32 v[144:145], v[144:145], v[152:153]
	s_nop 0
	v_pk_add_f32 v[144:145], v[154:155], v[144:145]
	s_nop 0
	v_add_f32_e32 v143, v144, v145
	v_and_b32_e32 v145, 64, v193
	v_xor_b32_e32 v144, 16, v193
	v_add_u32_e32 v145, 64, v145
	v_cmp_lt_i32_e32 vcc, v144, v145
	s_nop 1
	v_cndmask_b32_e32 v144, v193, v144, vcc
	v_lshlrev_b32_e32 v144, 2, v144
	v_mov_b32_e32 v144, v143
	s_nop 1
	v_permlane16_swap_b32_e32 v143, v144
	v_add_f32_e32 v143, v143, v144
	v_xor_b32_e32 v144, 32, v193
	v_cmp_lt_i32_e32 vcc, v144, v145
	s_nop 1
	v_cndmask_b32_e32 v144, v193, v144, vcc
	v_lshlrev_b32_e32 v144, 2, v144
	v_mov_b32_e32 v144, v143
	s_nop 1
	v_permlane32_swap_b32_e32 v143, v144
	v_add_f32_e32 v143, v143, v144
	v_fmamk_f32 v143, v143, 0x3c800000, v192
	v_rsq_f32_e32 v144, v143
.LBB0_775:
	v_add_u32_e32 v143, 0xa0, v178
	v_pk_mul_f32 v[64:65], v[64:65], v[144:145] op_sel_hi:[1,0]
	v_pk_mul_f32 v[152:153], v[62:63], v[144:145] op_sel_hi:[1,0]
	v_mov_b64_e32 v[156:157], s[58:59]
	v_pk_mul_f32 v[62:63], v[8:9], v[64:65]
	v_pk_mul_f32 v[64:65], v[6:7], v[152:153]
	v_pk_mul_f32 v[60:61], v[60:61], v[144:145] op_sel_hi:[1,0]
	v_pk_mul_f32 v[152:153], v[58:59], v[144:145] op_sel_hi:[1,0]
	v_mad_i64_i32 v[156:157], s[28:29], v143, s51, v[156:157]
	v_pk_mul_f32 v[58:59], v[4:5], v[60:61]
	v_pk_mul_f32 v[60:61], v[2:3], v[152:153]
	v_lshl_add_u64 v[156:157], s[26:27], 1, v[156:157]
	v_cvt_pk_f16_f32 v152, v64, v65
	v_cvt_pk_f16_f32 v153, v62, v63
	v_cvt_pk_f16_f32 v154, v60, v61
	v_cvt_pk_f16_f32 v155, v58, v59
	v_lshl_add_u64 v[156:157], v[24:25], 1, v[156:157]
	global_store_dwordx4 v[156:157], v[152:155], off
	v_pk_mul_f32 v[56:57], v[56:57], v[144:145] op_sel_hi:[1,0]
	v_pk_mul_f32 v[52:53], v[52:53], v[144:145] op_sel_hi:[1,0]
	v_pk_mul_f32 v[152:153], v[54:55], v[144:145] op_sel_hi:[1,0]
	v_pk_mul_f32 v[144:145], v[50:51], v[144:145] op_sel_hi:[1,0]
	v_pk_mul_f32 v[54:55], v[16:17], v[56:57]
	v_pk_mul_f32 v[56:57], v[14:15], v[152:153]
	v_pk_mul_f32 v[50:51], v[12:13], v[52:53]
	v_pk_mul_f32 v[52:53], v[10:11], v[144:145]
	v_cvt_pk_f16_f32 v152, v56, v57
	v_cvt_pk_f16_f32 v153, v54, v55
	v_cvt_pk_f16_f32 v154, v52, v53
	v_cvt_pk_f16_f32 v155, v50, v51
	global_store_dwordx4 v[156:157], v[152:155], off offset:64
	global_load_dword v143, v[180:181], off offset:704
	s_and_b64 vcc, exec, s[2:3]
	s_waitcnt vmcnt(0)
	v_fmamk_f32 v143, v143, 0x3a800000, v192
	v_rsq_f32_e32 v143, v143
	s_nop 0
	v_mul_f32_e32 v156, 0x39800000, v143
	v_pk_mul_f32 v[152:153], v[48:49], v[156:157] op_sel_hi:[1,0]
	v_pk_mul_f32 v[154:155], v[46:47], v[156:157] op_sel_hi:[1,0]
	v_pk_mul_f32 v[48:49], v[44:45], v[156:157] op_sel_hi:[1,0]
	v_pk_mul_f32 v[144:145], v[42:43], v[156:157] op_sel_hi:[1,0]
	v_pk_mul_f32 v[44:45], v[40:41], v[156:157] op_sel_hi:[1,0]
	v_pk_mul_f32 v[46:47], v[38:39], v[156:157] op_sel_hi:[1,0]
	v_pk_mul_f32 v[40:41], v[36:37], v[156:157] op_sel_hi:[1,0]
	v_pk_mul_f32 v[42:43], v[34:35], v[156:157] op_sel_hi:[1,0]
	s_cbranch_vccnz .LBB0_777
	v_pk_mul_f32 v[34:35], v[152:153], v[152:153]
	v_pk_mul_f32 v[36:37], v[154:155], v[154:155]
	s_nop 0
	v_pk_mov_b32 v[38:39], v[36:37], v[34:35] op_sel:[1,0]
	v_mov_b32_e32 v37, v35
	v_pk_add_f32 v[34:35], v[38:39], v[36:37]
	v_pk_mul_f32 v[36:37], v[48:49], v[48:49]
	v_pk_add_f32 v[34:35], v[34:35], v[34:35] op_sel_hi:[0,1]
	v_pk_mul_f32 v[38:39], v[144:145], v[144:145]
	v_mul_f32_e32 v34, v46, v46
	v_pk_mov_b32 v[142:143], v[38:39], v[36:37] op_sel:[1,0]
	v_mov_b32_e32 v39, v37
	v_pk_add_f32 v[36:37], v[142:143], v[38:39]
	v_pk_fma_f32 v[38:39], v[46:47], v[46:47], v[34:35] op_sel_hi:[1,1,0]
	v_mul_f32_e32 v34, v44, v44
	v_pk_add_f32 v[36:37], v[36:37], v[36:37] op_sel_hi:[0,1]
	v_pk_fma_f32 v[142:143], v[44:45], v[44:45], v[34:35] op_sel_hi:[1,1,0]
	v_mul_f32_e32 v38, v42, v42
	v_mul_f32_e32 v142, v43, v43
	v_mul_f32_e32 v34, v40, v40
	v_mul_f32_e32 v36, v41, v41
	v_pk_add_f32 v[38:39], v[38:39], v[142:143]
	v_pk_add_f32 v[34:35], v[34:35], v[36:37]
	v_and_b32_e32 v36, 64, v193
	v_pk_add_f32 v[34:35], v[38:39], v[34:35]
	v_add_u32_e32 v36, 64, v36
	v_add_f32_e32 v34, v34, v35
	v_xor_b32_e32 v35, 16, v193
	v_cmp_lt_i32_e32 vcc, v35, v36
	s_nop 1
	v_cndmask_b32_e32 v35, v193, v35, vcc
	v_lshlrev_b32_e32 v35, 2, v35
	v_mov_b32_e32 v35, v34
	s_nop 1
	v_permlane16_swap_b32_e32 v34, v35
	v_add_f32_e32 v34, v34, v35
	v_xor_b32_e32 v35, 32, v193
	v_cmp_lt_i32_e32 vcc, v35, v36
	s_nop 1
	v_cndmask_b32_e32 v35, v193, v35, vcc
	v_lshlrev_b32_e32 v35, 2, v35
	v_mov_b32_e32 v35, v34
	s_nop 1
	v_permlane32_swap_b32_e32 v34, v35
	v_add_f32_e32 v34, v34, v35
	v_fmamk_f32 v34, v34, 0x3c800000, v192
	v_rsq_f32_e32 v142, v34
